# v23 + the M0->LDS-DMA wait states in the other eight K-loops filled with ds_reads instead of s_nop (71 s_nop removed)
# speedup vs baseline: 1.0017x; 1.0005x over previous
.LBB0_425:
	v_add_u32_e32 v140, s67, v143
	ds_read_b128 v[146:149], v140
	ds_read_b128 v[150:153], v140 offset:1024
	ds_read_b128 v[154:157], v140 offset:2048
	ds_read_b128 v[158:161], v140 offset:3072
	v_add_u32_e32 v140, s68, v143
	ds_read_b128 v[162:165], v140
	ds_read_b128 v[166:169], v140 offset:1024
	ds_read_b128 v[170:173], v140 offset:2048
	ds_read_b128 v[174:177], v140 offset:3072
	s_add_i32 s13, s13, 2
	s_lshr_b32 s0, s13, 6
	s_mul_hi_u32 s1, s0, 0x8200000
	s_mul_i32 s0, s0, 0x8200000
	s_add_u32 s0, s46, s0
	s_addc_u32 s1, s47, s1
	s_and_b32 s35, s35, 0x1f00
	s_add_u32 s0, s0, s35
	s_addc_u32 s1, s1, 0
	s_add_u32 s0, s0, 0x100080
	s_addc_u32 s1, s1, 0
	s_add_i32 m0, s43, 0xc000
	ds_read_b128 v[178:181], v145
	ds_read_b128 v[182:185], v145 offset:1024
	ds_read_b128 v[186:189], v145 offset:2048
	ds_read_b128 v[190:193], v145 offset:3072
	ds_read_b128 v[194:197], v145 offset:4096
	ds_read_b128 v[198:201], v145 offset:5120
	ds_read_b128 v[202:205], v145 offset:6144
	global_load_lds_dwordx4 v128, s[0:1]
	s_add_i32 m0, s43, 0xe000
	ds_read_b128 v[206:209], v145 offset:7168
	global_load_lds_dwordx4 v132, s[0:1]
	s_waitcnt vmcnt(8)
	s_waitcnt lgkmcnt(0)
	s_setprio 3
	s_barrier
	v_mfma_f32_16x16x32_bf16 v[124:127], v[146:149], v[178:181], v[124:127]
	v_mfma_f32_16x16x32_bf16 v[120:123], v[154:157], v[178:181], v[120:123]
	v_mfma_f32_16x16x32_bf16 v[116:119], v[146:149], v[186:189], v[116:119]
	v_mfma_f32_16x16x32_bf16 v[108:111], v[154:157], v[186:189], v[108:111]
	v_mfma_f32_16x16x32_bf16 v[100:103], v[146:149], v[194:197], v[100:103]
	v_mfma_f32_16x16x32_bf16 v[92:95], v[154:157], v[194:197], v[92:95]
	v_mfma_f32_16x16x32_bf16 v[84:87], v[146:149], v[202:205], v[84:87]
	v_mfma_f32_16x16x32_bf16 v[76:79], v[154:157], v[202:205], v[76:79]
	v_mfma_f32_16x16x32_bf16 v[124:127], v[150:153], v[182:185], v[124:127]
	v_mfma_f32_16x16x32_bf16 v[120:123], v[158:161], v[182:185], v[120:123]
	v_mfma_f32_16x16x32_bf16 v[116:119], v[150:153], v[190:193], v[116:119]
	v_mfma_f32_16x16x32_bf16 v[108:111], v[158:161], v[190:193], v[108:111]
	v_mfma_f32_16x16x32_bf16 v[100:103], v[150:153], v[198:201], v[100:103]
	v_mfma_f32_16x16x32_bf16 v[92:95], v[158:161], v[198:201], v[92:95]
	v_mfma_f32_16x16x32_bf16 v[84:87], v[150:153], v[206:209], v[84:87]
	v_mfma_f32_16x16x32_bf16 v[76:79], v[158:161], v[206:209], v[76:79]
	s_setprio 0
	s_setprio 3
	v_mfma_f32_16x16x32_bf16 v[112:115], v[162:165], v[178:181], v[112:115]
	v_mfma_f32_16x16x32_bf16 v[104:107], v[170:173], v[178:181], v[104:107]
	v_mfma_f32_16x16x32_bf16 v[96:99], v[162:165], v[186:189], v[96:99]
	v_mfma_f32_16x16x32_bf16 v[88:91], v[170:173], v[186:189], v[88:91]
	v_mfma_f32_16x16x32_bf16 v[80:83], v[162:165], v[194:197], v[80:83]
	v_mfma_f32_16x16x32_bf16 v[72:75], v[170:173], v[194:197], v[72:75]
	v_mfma_f32_16x16x32_bf16 v[68:71], v[162:165], v[202:205], v[68:71]
	v_mfma_f32_16x16x32_bf16 v[64:67], v[170:173], v[202:205], v[64:67]
	v_mfma_f32_16x16x32_bf16 v[112:115], v[166:169], v[182:185], v[112:115]
	v_mfma_f32_16x16x32_bf16 v[104:107], v[174:177], v[182:185], v[104:107]
	v_mfma_f32_16x16x32_bf16 v[96:99], v[166:169], v[190:193], v[96:99]
	v_mfma_f32_16x16x32_bf16 v[88:91], v[174:177], v[190:193], v[88:91]
	v_mfma_f32_16x16x32_bf16 v[80:83], v[166:169], v[198:201], v[80:83]
	v_mfma_f32_16x16x32_bf16 v[72:75], v[174:177], v[198:201], v[72:75]
	v_mfma_f32_16x16x32_bf16 v[68:71], v[166:169], v[206:209], v[68:71]
	v_mfma_f32_16x16x32_bf16 v[64:67], v[174:177], v[206:209], v[64:67]
	s_barrier
	s_setprio 0
	s_add_i32 s0, s67, s59
	v_lshl_add_u64 v[140:141], s[52:53], 0, v[130:131]
	s_mov_b32 m0, s0
	ds_read_b128 v[178:181], v145 offset:16384
	ds_read_b128 v[182:185], v145 offset:17408
	ds_read_b128 v[186:189], v145 offset:18432
	ds_read_b128 v[190:193], v145 offset:19456
	ds_read_b128 v[194:197], v145 offset:20480
	global_load_lds_dwordx4 v[140:141], off
	s_add_i32 m0, s0, 0x2000
	s_add_u32 s0, s52, 0x100000
	v_lshl_add_u64 v[210:211], s[52:53], 0, v[134:135]
	s_addc_u32 s1, s53, 0
	s_add_i32 s35, s68, s59
	global_load_lds_dwordx4 v[210:211], off
	s_mov_b32 m0, s35
	v_lshl_add_u64 v[214:215], s[54:55], 0, v[132:133]
	global_load_lds_dwordx4 v130, s[0:1]
	s_add_i32 m0, s35, 0x2000
	ds_read_b128 v[206:209], v145 offset:23552
	global_load_lds_dwordx4 v134, s[0:1]
	v_lshl_add_u64 v[212:213], s[54:55], 0, v[128:129]
	s_mov_b32 m0, s43
	ds_read_b128 v[202:205], v145 offset:22528
	global_load_lds_dwordx4 v[212:213], off
	s_mov_b32 m0, s62
	ds_read_b128 v[198:201], v145 offset:21504
	global_load_lds_dwordx4 v[214:215], off
	s_waitcnt vmcnt(8)
	s_waitcnt lgkmcnt(0)
	s_setprio 3
	s_barrier
	v_mfma_f32_16x16x32_bf16 v[60:63], v[146:149], v[178:181], v[60:63]
	v_mfma_f32_16x16x32_bf16 v[56:59], v[154:157], v[178:181], v[56:59]
	v_mfma_f32_16x16x32_bf16 v[52:55], v[146:149], v[186:189], v[52:55]
	v_mfma_f32_16x16x32_bf16 v[44:47], v[154:157], v[186:189], v[44:47]
	v_mfma_f32_16x16x32_bf16 v[36:39], v[146:149], v[194:197], v[36:39]
	v_mfma_f32_16x16x32_bf16 v[28:31], v[154:157], v[194:197], v[28:31]
	v_mfma_f32_16x16x32_bf16 v[20:23], v[146:149], v[202:205], v[20:23]
	v_mfma_f32_16x16x32_bf16 v[12:15], v[154:157], v[202:205], v[12:15]
	v_mfma_f32_16x16x32_bf16 v[60:63], v[150:153], v[182:185], v[60:63]
	v_mfma_f32_16x16x32_bf16 v[56:59], v[158:161], v[182:185], v[56:59]
	v_mfma_f32_16x16x32_bf16 v[52:55], v[150:153], v[190:193], v[52:55]
	v_mfma_f32_16x16x32_bf16 v[44:47], v[158:161], v[190:193], v[44:47]
	v_mfma_f32_16x16x32_bf16 v[36:39], v[150:153], v[198:201], v[36:39]
	v_mfma_f32_16x16x32_bf16 v[28:31], v[158:161], v[198:201], v[28:31]
	v_mfma_f32_16x16x32_bf16 v[20:23], v[150:153], v[206:209], v[20:23]
	v_mfma_f32_16x16x32_bf16 v[12:15], v[158:161], v[206:209], v[12:15]
	s_setprio 0
	s_setprio 3
	v_mfma_f32_16x16x32_bf16 v[48:51], v[162:165], v[178:181], v[48:51]
	v_mfma_f32_16x16x32_bf16 v[40:43], v[170:173], v[178:181], v[40:43]
	v_mfma_f32_16x16x32_bf16 v[32:35], v[162:165], v[186:189], v[32:35]
	v_mfma_f32_16x16x32_bf16 v[24:27], v[170:173], v[186:189], v[24:27]
	v_mfma_f32_16x16x32_bf16 v[16:19], v[162:165], v[194:197], v[16:19]
	v_mfma_f32_16x16x32_bf16 v[8:11], v[170:173], v[194:197], v[8:11]
	v_mfma_f32_16x16x32_bf16 v[4:7], v[162:165], v[202:205], v[4:7]
	v_mfma_f32_16x16x32_bf16 v[0:3], v[170:173], v[202:205], v[0:3]
	v_mfma_f32_16x16x32_bf16 v[48:51], v[166:169], v[182:185], v[48:51]
	v_mfma_f32_16x16x32_bf16 v[40:43], v[174:177], v[182:185], v[40:43]
	v_mfma_f32_16x16x32_bf16 v[32:35], v[166:169], v[190:193], v[32:35]
	v_mfma_f32_16x16x32_bf16 v[24:27], v[174:177], v[190:193], v[24:27]
	v_mfma_f32_16x16x32_bf16 v[16:19], v[166:169], v[198:201], v[16:19]
	v_mfma_f32_16x16x32_bf16 v[8:11], v[174:177], v[198:201], v[8:11]
	v_mfma_f32_16x16x32_bf16 v[4:7], v[166:169], v[206:209], v[4:7]
	v_mfma_f32_16x16x32_bf16 v[0:3], v[174:177], v[206:209], v[0:3]
	s_barrier
	s_setprio 0
	s_add_i32 s35, 0, 0x18000
	s_add_i32 s37, 0, 0x1c000
	v_add_u32_e32 v158, s35, v143
	v_add_u32_e32 v174, s37, v143
	ds_read_b128 v[146:149], v158
	ds_read_b128 v[150:153], v158 offset:1024
	ds_read_b128 v[154:157], v158 offset:2048
	ds_read_b128 v[158:161], v158 offset:3072
	ds_read_b128 v[162:165], v174
	ds_read_b128 v[166:169], v174 offset:1024
	ds_read_b128 v[170:173], v174 offset:2048
	ds_read_b128 v[174:177], v174 offset:3072
	s_add_u32 s0, s54, 0x100000
	s_addc_u32 s1, s55, 0
	s_mov_b32 m0, s63
	ds_read_b128 v[178:181], v145 offset:32768
	ds_read_b128 v[182:185], v145 offset:33792
	ds_read_b128 v[186:189], v145 offset:34816
	ds_read_b128 v[190:193], v145 offset:35840
	ds_read_b128 v[194:197], v145 offset:36864
	ds_read_b128 v[198:201], v145 offset:37888
	ds_read_b128 v[202:205], v145 offset:38912
	global_load_lds_dwordx4 v128, s[0:1]
	s_mov_b32 m0, s64
	ds_read_b128 v[206:209], v145 offset:39936
	global_load_lds_dwordx4 v132, s[0:1]
	s_waitcnt vmcnt(8)
	s_waitcnt lgkmcnt(0)
	s_setprio 3
	s_barrier
	v_mfma_f32_16x16x32_bf16 v[124:127], v[146:149], v[178:181], v[124:127]
	v_mfma_f32_16x16x32_bf16 v[120:123], v[154:157], v[178:181], v[120:123]
	v_mfma_f32_16x16x32_bf16 v[116:119], v[146:149], v[186:189], v[116:119]
	v_mfma_f32_16x16x32_bf16 v[108:111], v[154:157], v[186:189], v[108:111]
	v_mfma_f32_16x16x32_bf16 v[100:103], v[146:149], v[194:197], v[100:103]
	v_mfma_f32_16x16x32_bf16 v[92:95], v[154:157], v[194:197], v[92:95]
	v_mfma_f32_16x16x32_bf16 v[84:87], v[146:149], v[202:205], v[84:87]
	v_mfma_f32_16x16x32_bf16 v[76:79], v[154:157], v[202:205], v[76:79]
	v_mfma_f32_16x16x32_bf16 v[124:127], v[150:153], v[182:185], v[124:127]
	v_mfma_f32_16x16x32_bf16 v[120:123], v[158:161], v[182:185], v[120:123]
	v_mfma_f32_16x16x32_bf16 v[116:119], v[150:153], v[190:193], v[116:119]
	v_mfma_f32_16x16x32_bf16 v[108:111], v[158:161], v[190:193], v[108:111]
	v_mfma_f32_16x16x32_bf16 v[100:103], v[150:153], v[198:201], v[100:103]
	v_mfma_f32_16x16x32_bf16 v[92:95], v[158:161], v[198:201], v[92:95]
	v_mfma_f32_16x16x32_bf16 v[84:87], v[150:153], v[206:209], v[84:87]
	v_mfma_f32_16x16x32_bf16 v[76:79], v[158:161], v[206:209], v[76:79]
	s_setprio 0
	s_setprio 3
	v_mfma_f32_16x16x32_bf16 v[112:115], v[162:165], v[178:181], v[112:115]
	v_mfma_f32_16x16x32_bf16 v[104:107], v[170:173], v[178:181], v[104:107]
	v_mfma_f32_16x16x32_bf16 v[96:99], v[162:165], v[186:189], v[96:99]
	v_mfma_f32_16x16x32_bf16 v[88:91], v[170:173], v[186:189], v[88:91]
	v_mfma_f32_16x16x32_bf16 v[80:83], v[162:165], v[194:197], v[80:83]
	v_mfma_f32_16x16x32_bf16 v[72:75], v[170:173], v[194:197], v[72:75]
	v_mfma_f32_16x16x32_bf16 v[68:71], v[162:165], v[202:205], v[68:71]
	v_mfma_f32_16x16x32_bf16 v[64:67], v[170:173], v[202:205], v[64:67]
	v_mfma_f32_16x16x32_bf16 v[112:115], v[166:169], v[182:185], v[112:115]
	v_mfma_f32_16x16x32_bf16 v[104:107], v[174:177], v[182:185], v[104:107]
	v_mfma_f32_16x16x32_bf16 v[96:99], v[166:169], v[190:193], v[96:99]
	v_mfma_f32_16x16x32_bf16 v[88:91], v[174:177], v[190:193], v[88:91]
	v_mfma_f32_16x16x32_bf16 v[80:83], v[166:169], v[198:201], v[80:83]
	v_mfma_f32_16x16x32_bf16 v[72:75], v[174:177], v[198:201], v[72:75]
	v_mfma_f32_16x16x32_bf16 v[68:71], v[166:169], v[206:209], v[68:71]
	v_mfma_f32_16x16x32_bf16 v[64:67], v[174:177], v[206:209], v[64:67]
	s_barrier
	s_setprio 0
	s_add_i32 s0, s35, s59
	v_lshl_add_u64 v[140:141], v[140:141], 0, s[14:15]
	s_mov_b32 m0, s0
	ds_read_b128 v[178:181], v145 offset:49152
	ds_read_b128 v[182:185], v145 offset:50176
	ds_read_b128 v[186:189], v145 offset:51200
	ds_read_b128 v[190:193], v145 offset:52224
	global_load_lds_dwordx4 v[140:141], off
	s_add_i32 m0, s0, 0x2000
	s_add_u32 s0, s52, 0x100080
	v_lshl_add_u64 v[140:141], v[210:211], 0, s[14:15]
	s_addc_u32 s1, s53, 0
	s_add_i32 s35, s37, s59
	global_load_lds_dwordx4 v[140:141], off
	s_mov_b32 m0, s35
	ds_read_b128 v[206:209], v145 offset:56320
	global_load_lds_dwordx4 v130, s[0:1]
	s_add_i32 m0, s35, 0x2000
	ds_read_b128 v[202:205], v145 offset:55296
	global_load_lds_dwordx4 v134, s[0:1]
	v_lshl_add_u64 v[140:141], v[212:213], 0, s[14:15]
	s_mov_b32 m0, s60
	ds_read_b128 v[198:201], v145 offset:54272
	global_load_lds_dwordx4 v[140:141], off
	v_lshl_add_u64 v[140:141], v[214:215], 0, s[14:15]
	s_mov_b32 m0, s65
	ds_read_b128 v[194:197], v145 offset:53248
	global_load_lds_dwordx4 v[140:141], off
	s_waitcnt vmcnt(8)
	s_waitcnt lgkmcnt(0)
	s_setprio 3
	s_barrier
	v_mfma_f32_16x16x32_bf16 v[60:63], v[146:149], v[178:181], v[60:63]
	v_mfma_f32_16x16x32_bf16 v[56:59], v[154:157], v[178:181], v[56:59]
	v_mfma_f32_16x16x32_bf16 v[52:55], v[146:149], v[186:189], v[52:55]
	v_mfma_f32_16x16x32_bf16 v[44:47], v[154:157], v[186:189], v[44:47]
	v_mfma_f32_16x16x32_bf16 v[36:39], v[146:149], v[194:197], v[36:39]
	v_mfma_f32_16x16x32_bf16 v[28:31], v[154:157], v[194:197], v[28:31]
	v_mfma_f32_16x16x32_bf16 v[20:23], v[146:149], v[202:205], v[20:23]
	v_mfma_f32_16x16x32_bf16 v[12:15], v[154:157], v[202:205], v[12:15]
	v_mfma_f32_16x16x32_bf16 v[60:63], v[150:153], v[182:185], v[60:63]
	v_mfma_f32_16x16x32_bf16 v[56:59], v[158:161], v[182:185], v[56:59]
	v_mfma_f32_16x16x32_bf16 v[52:55], v[150:153], v[190:193], v[52:55]
	v_mfma_f32_16x16x32_bf16 v[44:47], v[158:161], v[190:193], v[44:47]
	v_mfma_f32_16x16x32_bf16 v[36:39], v[150:153], v[198:201], v[36:39]
	v_mfma_f32_16x16x32_bf16 v[28:31], v[158:161], v[198:201], v[28:31]
	v_mfma_f32_16x16x32_bf16 v[20:23], v[150:153], v[206:209], v[20:23]
	v_mfma_f32_16x16x32_bf16 v[12:15], v[158:161], v[206:209], v[12:15]
	s_setprio 0
	s_setprio 3
	v_mfma_f32_16x16x32_bf16 v[48:51], v[162:165], v[178:181], v[48:51]
	v_mfma_f32_16x16x32_bf16 v[40:43], v[170:173], v[178:181], v[40:43]
	v_mfma_f32_16x16x32_bf16 v[32:35], v[162:165], v[186:189], v[32:35]
	v_mfma_f32_16x16x32_bf16 v[24:27], v[170:173], v[186:189], v[24:27]
	v_mfma_f32_16x16x32_bf16 v[16:19], v[162:165], v[194:197], v[16:19]
	v_mfma_f32_16x16x32_bf16 v[8:11], v[170:173], v[194:197], v[8:11]
	v_mfma_f32_16x16x32_bf16 v[4:7], v[162:165], v[202:205], v[4:7]
	v_mfma_f32_16x16x32_bf16 v[0:3], v[170:173], v[202:205], v[0:3]
	v_mfma_f32_16x16x32_bf16 v[48:51], v[166:169], v[182:185], v[48:51]
	v_mfma_f32_16x16x32_bf16 v[40:43], v[174:177], v[182:185], v[40:43]
	v_mfma_f32_16x16x32_bf16 v[32:35], v[166:169], v[190:193], v[32:35]
	v_mfma_f32_16x16x32_bf16 v[24:27], v[174:177], v[190:193], v[24:27]
	v_mfma_f32_16x16x32_bf16 v[16:19], v[166:169], v[198:201], v[16:19]
	v_mfma_f32_16x16x32_bf16 v[8:11], v[174:177], v[198:201], v[8:11]
	v_mfma_f32_16x16x32_bf16 v[4:7], v[166:169], v[206:209], v[4:7]
	v_mfma_f32_16x16x32_bf16 v[0:3], v[174:177], v[206:209], v[0:3]
	s_barrier
	s_setprio 0
	s_cmpk_gt_u32 s13, 0xa9
	s_mov_b32 s35, s4
	s_cbranch_scc1 .LBB0_432

.LBB0_677:
	ds_read_b128 v[156:159], v152
	ds_read_b128 v[160:163], v152 offset:1024
	ds_read_b128 v[164:167], v152 offset:2048
	ds_read_b128 v[168:171], v152 offset:3072
	ds_read_b128 v[172:175], v153
	ds_read_b128 v[176:179], v153 offset:1024
	ds_read_b128 v[180:183], v153 offset:2048
	ds_read_b128 v[184:187], v153 offset:3072
	s_add_u32 s0, s36, 0xfff00080
	s_addc_u32 s1, s37, -1
	s_cmp_eq_u32 s61, 60
	s_cselect_b32 s41, s56, s1
	s_cselect_b32 s40, s57, s0
	s_cselect_b32 s39, s15, s60
	s_cselect_b32 s38, s58, s59
	s_add_i32 m0, s31, 0xc000
	ds_read_b128 v[188:191], v154
	ds_read_b128 v[192:195], v154 offset:1024
	ds_read_b128 v[196:199], v154 offset:2048
	ds_read_b128 v[200:203], v154 offset:3072
	ds_read_b128 v[204:207], v154 offset:4096
	ds_read_b128 v[208:211], v154 offset:5120
	ds_read_b128 v[212:215], v154 offset:6144
	global_load_lds_dwordx4 v138, s[36:37]
	s_add_i32 m0, s31, 0xe000
	ds_read_b128 v[216:219], v154 offset:7168
	global_load_lds_dwordx4 v140, s[36:37]
	s_waitcnt vmcnt(8)
	s_waitcnt lgkmcnt(0)
	s_setprio 3
	s_barrier
	v_mfma_f32_16x16x32_bf16 v[124:127], v[156:159], v[188:191], v[124:127]
	v_mfma_f32_16x16x32_bf16 v[120:123], v[164:167], v[188:191], v[120:123]
	v_mfma_f32_16x16x32_bf16 v[108:111], v[156:159], v[196:199], v[108:111]
	v_mfma_f32_16x16x32_bf16 v[104:107], v[164:167], v[196:199], v[104:107]
	v_mfma_f32_16x16x32_bf16 v[92:95], v[156:159], v[204:207], v[92:95]
	v_mfma_f32_16x16x32_bf16 v[88:91], v[164:167], v[204:207], v[88:91]
	v_mfma_f32_16x16x32_bf16 v[76:79], v[156:159], v[212:215], v[76:79]
	v_mfma_f32_16x16x32_bf16 v[72:75], v[164:167], v[212:215], v[72:75]
	v_mfma_f32_16x16x32_bf16 v[124:127], v[160:163], v[192:195], v[124:127]
	v_mfma_f32_16x16x32_bf16 v[120:123], v[168:171], v[192:195], v[120:123]
	v_mfma_f32_16x16x32_bf16 v[108:111], v[160:163], v[200:203], v[108:111]
	v_mfma_f32_16x16x32_bf16 v[104:107], v[168:171], v[200:203], v[104:107]
	v_mfma_f32_16x16x32_bf16 v[92:95], v[160:163], v[208:211], v[92:95]
	v_mfma_f32_16x16x32_bf16 v[88:91], v[168:171], v[208:211], v[88:91]
	v_mfma_f32_16x16x32_bf16 v[76:79], v[160:163], v[216:219], v[76:79]
	v_mfma_f32_16x16x32_bf16 v[72:75], v[168:171], v[216:219], v[72:75]
	s_setprio 0
	s_setprio 3
	v_mfma_f32_16x16x32_bf16 v[116:119], v[172:175], v[188:191], v[116:119]
	v_mfma_f32_16x16x32_bf16 v[112:115], v[180:183], v[188:191], v[112:115]
	v_mfma_f32_16x16x32_bf16 v[100:103], v[172:175], v[196:199], v[100:103]
	v_mfma_f32_16x16x32_bf16 v[96:99], v[180:183], v[196:199], v[96:99]
	v_mfma_f32_16x16x32_bf16 v[84:87], v[172:175], v[204:207], v[84:87]
	v_mfma_f32_16x16x32_bf16 v[80:83], v[180:183], v[204:207], v[80:83]
	v_mfma_f32_16x16x32_bf16 v[68:71], v[172:175], v[212:215], v[68:71]
	v_mfma_f32_16x16x32_bf16 v[64:67], v[180:183], v[212:215], v[64:67]
	v_mfma_f32_16x16x32_bf16 v[116:119], v[176:179], v[192:195], v[116:119]
	v_mfma_f32_16x16x32_bf16 v[112:115], v[184:187], v[192:195], v[112:115]
	v_mfma_f32_16x16x32_bf16 v[100:103], v[176:179], v[200:203], v[100:103]
	v_mfma_f32_16x16x32_bf16 v[96:99], v[184:187], v[200:203], v[96:99]
	v_mfma_f32_16x16x32_bf16 v[84:87], v[176:179], v[208:211], v[84:87]
	v_mfma_f32_16x16x32_bf16 v[80:83], v[184:187], v[208:211], v[80:83]
	v_mfma_f32_16x16x32_bf16 v[68:71], v[176:179], v[216:219], v[68:71]
	v_mfma_f32_16x16x32_bf16 v[64:67], v[184:187], v[216:219], v[64:67]
	s_barrier
	s_setprio 0
	s_add_i32 s0, s51, s43
	v_lshl_add_u64 v[146:147], s[38:39], 0, v[130:131]
	s_mov_b32 m0, s0
	ds_read_b128 v[188:191], v154 offset:16384
	ds_read_b128 v[192:195], v154 offset:17408
	ds_read_b128 v[196:199], v154 offset:18432
	ds_read_b128 v[200:203], v154 offset:19456
	ds_read_b128 v[204:207], v154 offset:20480
	global_load_lds_dwordx4 v[146:147], off
	s_add_i32 m0, s0, 0x2000
	s_add_u32 s0, s38, 0x100000
	v_lshl_add_u64 v[220:221], s[38:39], 0, v[134:135]
	s_addc_u32 s1, s39, 0
	s_add_i32 s62, s52, s43
	global_load_lds_dwordx4 v[220:221], off
	s_mov_b32 m0, s62
	v_lshl_add_u64 v[224:225], s[40:41], 0, v[132:133]
	global_load_lds_dwordx4 v130, s[0:1]
	s_add_i32 m0, s62, 0x2000
	ds_read_b128 v[216:219], v154 offset:23552
	global_load_lds_dwordx4 v134, s[0:1]
	v_lshl_add_u64 v[222:223], s[40:41], 0, v[128:129]
	s_mov_b32 m0, s31
	ds_read_b128 v[212:215], v154 offset:22528
	global_load_lds_dwordx4 v[222:223], off
	s_mov_b32 m0, s35
	ds_read_b128 v[208:211], v154 offset:21504
	global_load_lds_dwordx4 v[224:225], off
	s_waitcnt vmcnt(8)
	s_waitcnt lgkmcnt(0)
	s_setprio 3
	s_barrier
	v_mfma_f32_16x16x32_bf16 v[60:63], v[156:159], v[188:191], v[60:63]
	v_mfma_f32_16x16x32_bf16 v[56:59], v[164:167], v[188:191], v[56:59]
	v_mfma_f32_16x16x32_bf16 v[44:47], v[156:159], v[196:199], v[44:47]
	v_mfma_f32_16x16x32_bf16 v[40:43], v[164:167], v[196:199], v[40:43]
	v_mfma_f32_16x16x32_bf16 v[28:31], v[156:159], v[204:207], v[28:31]
	v_mfma_f32_16x16x32_bf16 v[24:27], v[164:167], v[204:207], v[24:27]
	v_mfma_f32_16x16x32_bf16 v[12:15], v[156:159], v[212:215], v[12:15]
	v_mfma_f32_16x16x32_bf16 v[8:11], v[164:167], v[212:215], v[8:11]
	v_mfma_f32_16x16x32_bf16 v[60:63], v[160:163], v[192:195], v[60:63]
	v_mfma_f32_16x16x32_bf16 v[56:59], v[168:171], v[192:195], v[56:59]
	v_mfma_f32_16x16x32_bf16 v[44:47], v[160:163], v[200:203], v[44:47]
	v_mfma_f32_16x16x32_bf16 v[40:43], v[168:171], v[200:203], v[40:43]
	v_mfma_f32_16x16x32_bf16 v[28:31], v[160:163], v[208:211], v[28:31]
	v_mfma_f32_16x16x32_bf16 v[24:27], v[168:171], v[208:211], v[24:27]
	v_mfma_f32_16x16x32_bf16 v[12:15], v[160:163], v[216:219], v[12:15]
	v_mfma_f32_16x16x32_bf16 v[8:11], v[168:171], v[216:219], v[8:11]
	s_setprio 0
	s_setprio 3
	v_mfma_f32_16x16x32_bf16 v[52:55], v[172:175], v[188:191], v[52:55]
	v_mfma_f32_16x16x32_bf16 v[48:51], v[180:183], v[188:191], v[48:51]
	v_mfma_f32_16x16x32_bf16 v[36:39], v[172:175], v[196:199], v[36:39]
	v_mfma_f32_16x16x32_bf16 v[32:35], v[180:183], v[196:199], v[32:35]
	v_mfma_f32_16x16x32_bf16 v[20:23], v[172:175], v[204:207], v[20:23]
	v_mfma_f32_16x16x32_bf16 v[16:19], v[180:183], v[204:207], v[16:19]
	v_mfma_f32_16x16x32_bf16 v[4:7], v[172:175], v[212:215], v[4:7]
	v_mfma_f32_16x16x32_bf16 v[0:3], v[180:183], v[212:215], v[0:3]
	v_mfma_f32_16x16x32_bf16 v[52:55], v[176:179], v[192:195], v[52:55]
	v_mfma_f32_16x16x32_bf16 v[48:51], v[184:187], v[192:195], v[48:51]
	v_mfma_f32_16x16x32_bf16 v[36:39], v[176:179], v[200:203], v[36:39]
	v_mfma_f32_16x16x32_bf16 v[32:35], v[184:187], v[200:203], v[32:35]
	v_mfma_f32_16x16x32_bf16 v[20:23], v[176:179], v[208:211], v[20:23]
	v_mfma_f32_16x16x32_bf16 v[16:19], v[184:187], v[208:211], v[16:19]
	v_mfma_f32_16x16x32_bf16 v[4:7], v[176:179], v[216:219], v[4:7]
	v_mfma_f32_16x16x32_bf16 v[0:3], v[184:187], v[216:219], v[0:3]
	s_barrier
	s_setprio 0
	s_add_i32 s62, 0, 0x18000
	v_add_u32_e32 v155, s62, v149
	s_add_i32 s63, 0, 0x1c000
	ds_read_b128 v[156:159], v155
	ds_read_b128 v[160:163], v155 offset:1024
	ds_read_b128 v[164:167], v155 offset:2048
	ds_read_b128 v[168:171], v155 offset:3072
	v_add_u32_e32 v155, s63, v149
	ds_read_b128 v[172:175], v155
	ds_read_b128 v[176:179], v155 offset:1024
	ds_read_b128 v[180:183], v155 offset:2048
	ds_read_b128 v[184:187], v155 offset:3072
	s_add_u32 s0, s40, 0x100000
	s_addc_u32 s1, s41, 0
	s_mov_b32 m0, s44
	ds_read_b128 v[188:191], v154 offset:32768
	ds_read_b128 v[192:195], v154 offset:33792
	ds_read_b128 v[196:199], v154 offset:34816
	ds_read_b128 v[200:203], v154 offset:35840
	ds_read_b128 v[204:207], v154 offset:36864
	ds_read_b128 v[208:211], v154 offset:37888
	ds_read_b128 v[212:215], v154 offset:38912
	global_load_lds_dwordx4 v128, s[0:1]
	s_mov_b32 m0, s45
	ds_read_b128 v[216:219], v154 offset:39936
	global_load_lds_dwordx4 v132, s[0:1]
	s_waitcnt vmcnt(8)
	s_waitcnt lgkmcnt(0)
	s_setprio 3
	s_barrier
	v_mfma_f32_16x16x32_bf16 v[124:127], v[156:159], v[188:191], v[124:127]
	v_mfma_f32_16x16x32_bf16 v[120:123], v[164:167], v[188:191], v[120:123]
	v_mfma_f32_16x16x32_bf16 v[108:111], v[156:159], v[196:199], v[108:111]
	v_mfma_f32_16x16x32_bf16 v[104:107], v[164:167], v[196:199], v[104:107]
	v_mfma_f32_16x16x32_bf16 v[92:95], v[156:159], v[204:207], v[92:95]
	v_mfma_f32_16x16x32_bf16 v[88:91], v[164:167], v[204:207], v[88:91]
	v_mfma_f32_16x16x32_bf16 v[76:79], v[156:159], v[212:215], v[76:79]
	v_mfma_f32_16x16x32_bf16 v[72:75], v[164:167], v[212:215], v[72:75]
	v_mfma_f32_16x16x32_bf16 v[124:127], v[160:163], v[192:195], v[124:127]
	v_mfma_f32_16x16x32_bf16 v[120:123], v[168:171], v[192:195], v[120:123]
	v_mfma_f32_16x16x32_bf16 v[108:111], v[160:163], v[200:203], v[108:111]
	v_mfma_f32_16x16x32_bf16 v[104:107], v[168:171], v[200:203], v[104:107]
	v_mfma_f32_16x16x32_bf16 v[92:95], v[160:163], v[208:211], v[92:95]
	v_mfma_f32_16x16x32_bf16 v[88:91], v[168:171], v[208:211], v[88:91]
	v_mfma_f32_16x16x32_bf16 v[76:79], v[160:163], v[216:219], v[76:79]
	v_mfma_f32_16x16x32_bf16 v[72:75], v[168:171], v[216:219], v[72:75]
	s_setprio 0
	s_setprio 3
	v_mfma_f32_16x16x32_bf16 v[116:119], v[172:175], v[188:191], v[116:119]
	v_mfma_f32_16x16x32_bf16 v[112:115], v[180:183], v[188:191], v[112:115]
	v_mfma_f32_16x16x32_bf16 v[100:103], v[172:175], v[196:199], v[100:103]
	v_mfma_f32_16x16x32_bf16 v[96:99], v[180:183], v[196:199], v[96:99]
	v_mfma_f32_16x16x32_bf16 v[84:87], v[172:175], v[204:207], v[84:87]
	v_mfma_f32_16x16x32_bf16 v[80:83], v[180:183], v[204:207], v[80:83]
	v_mfma_f32_16x16x32_bf16 v[68:71], v[172:175], v[212:215], v[68:71]
	v_mfma_f32_16x16x32_bf16 v[64:67], v[180:183], v[212:215], v[64:67]
	v_mfma_f32_16x16x32_bf16 v[116:119], v[176:179], v[192:195], v[116:119]
	v_mfma_f32_16x16x32_bf16 v[112:115], v[184:187], v[192:195], v[112:115]
	v_mfma_f32_16x16x32_bf16 v[100:103], v[176:179], v[200:203], v[100:103]
	v_mfma_f32_16x16x32_bf16 v[96:99], v[184:187], v[200:203], v[96:99]
	v_mfma_f32_16x16x32_bf16 v[84:87], v[176:179], v[208:211], v[84:87]
	v_mfma_f32_16x16x32_bf16 v[80:83], v[184:187], v[208:211], v[80:83]
	v_mfma_f32_16x16x32_bf16 v[68:71], v[176:179], v[216:219], v[68:71]
	v_mfma_f32_16x16x32_bf16 v[64:67], v[184:187], v[216:219], v[64:67]
	s_barrier
	s_setprio 0
	s_add_i32 s0, s62, s43
	v_lshl_add_u64 v[146:147], v[146:147], 0, s[10:11]
	s_mov_b32 m0, s0
	ds_read_b128 v[188:191], v154 offset:49152
	ds_read_b128 v[192:195], v154 offset:50176
	ds_read_b128 v[196:199], v154 offset:51200
	ds_read_b128 v[200:203], v154 offset:52224
	global_load_lds_dwordx4 v[146:147], off
	s_add_i32 m0, s0, 0x2000
	s_add_u32 s0, s38, 0x100080
	v_lshl_add_u64 v[146:147], v[220:221], 0, s[10:11]
	s_addc_u32 s1, s39, 0
	s_add_i32 s38, s63, s43
	global_load_lds_dwordx4 v[146:147], off
	s_mov_b32 m0, s38
	ds_read_b128 v[216:219], v154 offset:56320
	global_load_lds_dwordx4 v130, s[0:1]
	s_add_i32 m0, s38, 0x2000
	ds_read_b128 v[212:215], v154 offset:55296
	global_load_lds_dwordx4 v134, s[0:1]
	v_lshl_add_u64 v[146:147], v[222:223], 0, s[10:11]
	s_mov_b32 m0, s46
	ds_read_b128 v[208:211], v154 offset:54272
	global_load_lds_dwordx4 v[146:147], off
	v_lshl_add_u64 v[146:147], v[224:225], 0, s[10:11]
	s_mov_b32 m0, s47
	ds_read_b128 v[204:207], v154 offset:53248
	global_load_lds_dwordx4 v[146:147], off
	s_waitcnt vmcnt(8)
	s_waitcnt lgkmcnt(0)
	s_setprio 3
	s_barrier
	v_mfma_f32_16x16x32_bf16 v[60:63], v[156:159], v[188:191], v[60:63]
	v_mfma_f32_16x16x32_bf16 v[56:59], v[164:167], v[188:191], v[56:59]
	v_mfma_f32_16x16x32_bf16 v[44:47], v[156:159], v[196:199], v[44:47]
	v_mfma_f32_16x16x32_bf16 v[40:43], v[164:167], v[196:199], v[40:43]
	v_mfma_f32_16x16x32_bf16 v[28:31], v[156:159], v[204:207], v[28:31]
	v_mfma_f32_16x16x32_bf16 v[24:27], v[164:167], v[204:207], v[24:27]
	v_mfma_f32_16x16x32_bf16 v[12:15], v[156:159], v[212:215], v[12:15]
	v_mfma_f32_16x16x32_bf16 v[8:11], v[164:167], v[212:215], v[8:11]
	v_mfma_f32_16x16x32_bf16 v[60:63], v[160:163], v[192:195], v[60:63]
	v_mfma_f32_16x16x32_bf16 v[56:59], v[168:171], v[192:195], v[56:59]
	v_mfma_f32_16x16x32_bf16 v[44:47], v[160:163], v[200:203], v[44:47]
	v_mfma_f32_16x16x32_bf16 v[40:43], v[168:171], v[200:203], v[40:43]
	v_mfma_f32_16x16x32_bf16 v[28:31], v[160:163], v[208:211], v[28:31]
	v_mfma_f32_16x16x32_bf16 v[24:27], v[168:171], v[208:211], v[24:27]
	v_mfma_f32_16x16x32_bf16 v[12:15], v[160:163], v[216:219], v[12:15]
	v_mfma_f32_16x16x32_bf16 v[8:11], v[168:171], v[216:219], v[8:11]
	s_setprio 0
	s_setprio 3
	v_mfma_f32_16x16x32_bf16 v[52:55], v[172:175], v[188:191], v[52:55]
	v_mfma_f32_16x16x32_bf16 v[48:51], v[180:183], v[188:191], v[48:51]
	v_mfma_f32_16x16x32_bf16 v[36:39], v[172:175], v[196:199], v[36:39]
	v_mfma_f32_16x16x32_bf16 v[32:35], v[180:183], v[196:199], v[32:35]
	v_mfma_f32_16x16x32_bf16 v[20:23], v[172:175], v[204:207], v[20:23]
	v_mfma_f32_16x16x32_bf16 v[16:19], v[180:183], v[204:207], v[16:19]
	v_mfma_f32_16x16x32_bf16 v[4:7], v[172:175], v[212:215], v[4:7]
	v_mfma_f32_16x16x32_bf16 v[0:3], v[180:183], v[212:215], v[0:3]
	v_mfma_f32_16x16x32_bf16 v[52:55], v[176:179], v[192:195], v[52:55]
	v_mfma_f32_16x16x32_bf16 v[48:51], v[184:187], v[192:195], v[48:51]
	v_mfma_f32_16x16x32_bf16 v[36:39], v[176:179], v[200:203], v[36:39]
	v_mfma_f32_16x16x32_bf16 v[32:35], v[184:187], v[200:203], v[32:35]
	v_mfma_f32_16x16x32_bf16 v[20:23], v[176:179], v[208:211], v[20:23]
	v_mfma_f32_16x16x32_bf16 v[16:19], v[184:187], v[208:211], v[16:19]
	v_mfma_f32_16x16x32_bf16 v[4:7], v[176:179], v[216:219], v[4:7]
	v_mfma_f32_16x16x32_bf16 v[0:3], v[184:187], v[216:219], v[0:3]
	s_barrier
	s_setprio 0
	s_add_u32 s36, s36, 0x100
	s_addc_u32 s37, s37, 0
	s_add_i32 s61, s61, 2
	s_add_u32 s59, s59, 0x100
	s_addc_u32 s60, s60, 0
	s_cmp_gt_u32 s61, 61
	s_cbranch_scc0 .LBB0_677
	s_and_b64 vcc, exec, s[12:13]
	s_cbranch_vccz .LBB0_680
	s_barrier

.LBB0_705:
	ds_read_b128 v[24:27], v191
	ds_read_b128 v[28:31], v191 offset:1024
	ds_read_b128 v[16:19], v191 offset:2048
	ds_read_b128 v[20:23], v191 offset:3072
	ds_read_b128 v[8:11], v192
	ds_read_b128 v[12:15], v192 offset:1024
	ds_read_b128 v[0:3], v192 offset:2048
	ds_read_b128 v[4:7], v192 offset:3072
	s_add_u32 s0, s44, 0xfff80080
	s_addc_u32 s1, s45, -1
	s_cmp_eq_u32 s70, 28
	s_cselect_b32 s49, s60, s1
	s_cselect_b32 s48, s66, s0
	s_cselect_b32 s47, s31, s69
	s_cselect_b32 s46, s67, s68
	s_add_i32 m0, s41, 0xc000
	ds_read_b128 v[178:181], v193
	ds_read_b128 v[182:185], v193 offset:1024
	ds_read_b128 v[194:197], v193 offset:2048
	ds_read_b128 v[198:201], v193 offset:3072
	ds_read_b128 v[208:211], v193 offset:4096
	ds_read_b128 v[212:215], v193 offset:5120
	ds_read_b128 v[216:219], v193 offset:6144
	global_load_lds_dwordx4 v170, s[44:45]
	s_add_i32 m0, s41, 0xe000
	ds_read_b128 v[220:223], v193 offset:7168
	global_load_lds_dwordx4 v172, s[44:45]
	s_waitcnt vmcnt(8)
	s_waitcnt lgkmcnt(0)
	s_setprio 3
	s_barrier
	v_mfma_scale_f32_16x16x128_f8f6f4 v[156:159], v[24:31], v[178:185], v[156:159], v186, v186 op_sel_hi:[0,0,0]
	v_mfma_scale_f32_16x16x128_f8f6f4 v[152:155], v[16:23], v[178:185], v[152:155], v186, v186 op_sel_hi:[0,0,0]
	v_mfma_scale_f32_16x16x128_f8f6f4 v[140:143], v[24:31], v[194:201], v[140:143], v186, v186 op_sel_hi:[0,0,0]
	v_mfma_scale_f32_16x16x128_f8f6f4 v[136:139], v[16:23], v[194:201], v[136:139], v186, v186 op_sel_hi:[0,0,0]
	v_mfma_scale_f32_16x16x128_f8f6f4 v[124:127], v[24:31], v[208:215], v[124:127], v186, v186 op_sel_hi:[0,0,0]
	v_mfma_scale_f32_16x16x128_f8f6f4 v[120:123], v[16:23], v[208:215], v[120:123], v186, v186 op_sel_hi:[0,0,0]
	v_mfma_scale_f32_16x16x128_f8f6f4 v[108:111], v[24:31], v[216:223], v[108:111], v186, v186 op_sel_hi:[0,0,0]
	v_mfma_scale_f32_16x16x128_f8f6f4 v[104:107], v[16:23], v[216:223], v[104:107], v186, v186 op_sel_hi:[0,0,0]
	s_setprio 0
	s_setprio 3
	v_mfma_scale_f32_16x16x128_f8f6f4 v[148:151], v[8:15], v[178:185], v[148:151], v186, v186 op_sel_hi:[0,0,0]
	v_mfma_scale_f32_16x16x128_f8f6f4 v[144:147], v[0:7], v[178:185], v[144:147], v186, v186 op_sel_hi:[0,0,0]
	v_mfma_scale_f32_16x16x128_f8f6f4 v[132:135], v[8:15], v[194:201], v[132:135], v186, v186 op_sel_hi:[0,0,0]
	v_mfma_scale_f32_16x16x128_f8f6f4 v[128:131], v[0:7], v[194:201], v[128:131], v186, v186 op_sel_hi:[0,0,0]
	v_mfma_scale_f32_16x16x128_f8f6f4 v[116:119], v[8:15], v[208:215], v[116:119], v186, v186 op_sel_hi:[0,0,0]
	v_mfma_scale_f32_16x16x128_f8f6f4 v[112:115], v[0:7], v[208:215], v[112:115], v186, v186 op_sel_hi:[0,0,0]
	v_mfma_scale_f32_16x16x128_f8f6f4 v[100:103], v[8:15], v[216:223], v[100:103], v186, v186 op_sel_hi:[0,0,0]
	v_mfma_scale_f32_16x16x128_f8f6f4 v[96:99], v[0:7], v[216:223], v[96:99], v186, v186 op_sel_hi:[0,0,0]
	s_barrier
	s_setprio 0
	s_add_i32 s0, s58, s51
	v_lshl_add_u64 v[178:179], s[46:47], 0, v[162:163]
	s_mov_b32 m0, s0
	ds_read_b128 v[194:197], v193 offset:16384
	ds_read_b128 v[198:201], v193 offset:17408
	ds_read_b128 v[208:211], v193 offset:18432
	ds_read_b128 v[212:215], v193 offset:19456
	ds_read_b128 v[216:219], v193 offset:20480
	global_load_lds_dwordx4 v[178:179], off
	s_add_i32 m0, s0, 0x2000
	s_add_u32 s0, s46, 0x80000
	v_lshl_add_u64 v[180:181], s[46:47], 0, v[166:167]
	s_addc_u32 s1, s47, 0
	s_add_i32 s71, s59, s51
	global_load_lds_dwordx4 v[180:181], off
	s_mov_b32 m0, s71
	v_lshl_add_u64 v[184:185], s[48:49], 0, v[164:165]
	global_load_lds_dwordx4 v162, s[0:1]
	s_add_i32 m0, s71, 0x2000
	ds_read_b128 v[228:231], v193 offset:23552
	global_load_lds_dwordx4 v166, s[0:1]
	v_lshl_add_u64 v[182:183], s[48:49], 0, v[160:161]
	s_mov_b32 m0, s41
	ds_read_b128 v[224:227], v193 offset:22528
	global_load_lds_dwordx4 v[182:183], off
	s_mov_b32 m0, s43
	ds_read_b128 v[220:223], v193 offset:21504
	global_load_lds_dwordx4 v[184:185], off
	s_waitcnt vmcnt(8)
	s_waitcnt lgkmcnt(0)
	s_setprio 3
	s_barrier
	v_mfma_scale_f32_16x16x128_f8f6f4 v[92:95], v[24:31], v[194:201], v[92:95], v186, v186 op_sel_hi:[0,0,0]
	v_mfma_scale_f32_16x16x128_f8f6f4 v[88:91], v[16:23], v[194:201], v[88:91], v186, v186 op_sel_hi:[0,0,0]
	v_mfma_scale_f32_16x16x128_f8f6f4 v[80:83], v[24:31], v[208:215], v[80:83], v186, v186 op_sel_hi:[0,0,0]
	v_mfma_scale_f32_16x16x128_f8f6f4 v[72:75], v[16:23], v[208:215], v[72:75], v186, v186 op_sel_hi:[0,0,0]
	v_mfma_scale_f32_16x16x128_f8f6f4 v[64:67], v[24:31], v[216:223], v[64:67], v186, v186 op_sel_hi:[0,0,0]
	v_mfma_scale_f32_16x16x128_f8f6f4 v[56:59], v[16:23], v[216:223], v[56:59], v186, v186 op_sel_hi:[0,0,0]
	v_mfma_scale_f32_16x16x128_f8f6f4 v[48:51], v[24:31], v[224:231], v[48:51], v186, v186 op_sel_hi:[0,0,0]
	v_mfma_scale_f32_16x16x128_f8f6f4 v[40:43], v[16:23], v[224:231], v[40:43], v186, v186 op_sel_hi:[0,0,0]
	s_setprio 0
	s_setprio 3
	v_mfma_scale_f32_16x16x128_f8f6f4 v[84:87], v[8:15], v[194:201], v[84:87], v186, v186 op_sel_hi:[0,0,0]
	v_mfma_scale_f32_16x16x128_f8f6f4 v[76:79], v[0:7], v[194:201], v[76:79], v186, v186 op_sel_hi:[0,0,0]
	v_mfma_scale_f32_16x16x128_f8f6f4 v[68:71], v[8:15], v[208:215], v[68:71], v186, v186 op_sel_hi:[0,0,0]
	v_mfma_scale_f32_16x16x128_f8f6f4 v[60:63], v[0:7], v[208:215], v[60:63], v186, v186 op_sel_hi:[0,0,0]
	v_mfma_scale_f32_16x16x128_f8f6f4 v[52:55], v[8:15], v[216:223], v[52:55], v186, v186 op_sel_hi:[0,0,0]
	v_mfma_scale_f32_16x16x128_f8f6f4 v[44:47], v[0:7], v[216:223], v[44:47], v186, v186 op_sel_hi:[0,0,0]
	v_mfma_scale_f32_16x16x128_f8f6f4 v[36:39], v[8:15], v[224:231], v[36:39], v186, v186 op_sel_hi:[0,0,0]
	v_mfma_scale_f32_16x16x128_f8f6f4 v[32:35], v[0:7], v[224:231], v[32:35], v186, v186 op_sel_hi:[0,0,0]
	s_barrier
	s_setprio 0
	s_add_i32 s71, 0, 0x18000
	s_add_i32 s73, 0, 0x1c000
	v_add_u32_e32 v12, s71, v188
	v_add_u32_e32 v28, s73, v188
	ds_read_b128 v[0:3], v12
	ds_read_b128 v[4:7], v12 offset:1024
	ds_read_b128 v[8:11], v12 offset:2048
	ds_read_b128 v[12:15], v12 offset:3072
	ds_read_b128 v[16:19], v28
	ds_read_b128 v[20:23], v28 offset:1024
	ds_read_b128 v[24:27], v28 offset:2048
	ds_read_b128 v[28:31], v28 offset:3072
	s_add_u32 s0, s48, 0x80000
	s_addc_u32 s1, s49, 0
	s_mov_b32 m0, s52
	ds_read_b128 v[194:197], v193 offset:32768
	ds_read_b128 v[198:201], v193 offset:33792
	ds_read_b128 v[208:211], v193 offset:34816
	ds_read_b128 v[212:215], v193 offset:35840
	ds_read_b128 v[216:219], v193 offset:36864
	ds_read_b128 v[220:223], v193 offset:37888
	ds_read_b128 v[224:227], v193 offset:38912
	global_load_lds_dwordx4 v160, s[0:1]
	s_mov_b32 m0, s53
	ds_read_b128 v[228:231], v193 offset:39936
	global_load_lds_dwordx4 v164, s[0:1]
	s_waitcnt vmcnt(8)
	s_waitcnt lgkmcnt(0)
	s_setprio 3
	s_barrier
	v_mfma_scale_f32_16x16x128_f8f6f4 v[156:159], v[0:7], v[194:201], v[156:159], v186, v186 op_sel_hi:[0,0,0]
	v_mfma_scale_f32_16x16x128_f8f6f4 v[152:155], v[8:15], v[194:201], v[152:155], v186, v186 op_sel_hi:[0,0,0]
	v_mfma_scale_f32_16x16x128_f8f6f4 v[140:143], v[0:7], v[208:215], v[140:143], v186, v186 op_sel_hi:[0,0,0]
	v_mfma_scale_f32_16x16x128_f8f6f4 v[136:139], v[8:15], v[208:215], v[136:139], v186, v186 op_sel_hi:[0,0,0]
	v_mfma_scale_f32_16x16x128_f8f6f4 v[124:127], v[0:7], v[216:223], v[124:127], v186, v186 op_sel_hi:[0,0,0]
	v_mfma_scale_f32_16x16x128_f8f6f4 v[120:123], v[8:15], v[216:223], v[120:123], v186, v186 op_sel_hi:[0,0,0]
	v_mfma_scale_f32_16x16x128_f8f6f4 v[108:111], v[0:7], v[224:231], v[108:111], v186, v186 op_sel_hi:[0,0,0]
	v_mfma_scale_f32_16x16x128_f8f6f4 v[104:107], v[8:15], v[224:231], v[104:107], v186, v186 op_sel_hi:[0,0,0]
	s_setprio 0
	s_setprio 3
	v_mfma_scale_f32_16x16x128_f8f6f4 v[148:151], v[16:23], v[194:201], v[148:151], v186, v186 op_sel_hi:[0,0,0]
	v_mfma_scale_f32_16x16x128_f8f6f4 v[144:147], v[24:31], v[194:201], v[144:147], v186, v186 op_sel_hi:[0,0,0]
	v_mfma_scale_f32_16x16x128_f8f6f4 v[132:135], v[16:23], v[208:215], v[132:135], v186, v186 op_sel_hi:[0,0,0]
	v_mfma_scale_f32_16x16x128_f8f6f4 v[128:131], v[24:31], v[208:215], v[128:131], v186, v186 op_sel_hi:[0,0,0]
	v_mfma_scale_f32_16x16x128_f8f6f4 v[116:119], v[16:23], v[216:223], v[116:119], v186, v186 op_sel_hi:[0,0,0]
	v_mfma_scale_f32_16x16x128_f8f6f4 v[112:115], v[24:31], v[216:223], v[112:115], v186, v186 op_sel_hi:[0,0,0]
	v_mfma_scale_f32_16x16x128_f8f6f4 v[100:103], v[16:23], v[224:231], v[100:103], v186, v186 op_sel_hi:[0,0,0]
	v_mfma_scale_f32_16x16x128_f8f6f4 v[96:99], v[24:31], v[224:231], v[96:99], v186, v186 op_sel_hi:[0,0,0]
	s_barrier
	s_setprio 0
	s_add_i32 s0, s71, s51
	v_lshl_add_u64 v[178:179], v[178:179], 0, s[10:11]
	s_mov_b32 m0, s0
	ds_read_b128 v[194:197], v193 offset:49152
	ds_read_b128 v[198:201], v193 offset:50176
	ds_read_b128 v[208:211], v193 offset:51200
	ds_read_b128 v[212:215], v193 offset:52224
	global_load_lds_dwordx4 v[178:179], off
	s_add_i32 m0, s0, 0x2000
	s_add_u32 s0, s46, 0x80080
	v_lshl_add_u64 v[178:179], v[180:181], 0, s[10:11]
	s_addc_u32 s1, s47, 0
	s_add_i32 s46, s73, s51
	global_load_lds_dwordx4 v[178:179], off
	s_mov_b32 m0, s46
	ds_read_b128 v[228:231], v193 offset:56320
	global_load_lds_dwordx4 v162, s[0:1]
	s_add_i32 m0, s46, 0x2000
	ds_read_b128 v[224:227], v193 offset:55296
	global_load_lds_dwordx4 v166, s[0:1]
	v_lshl_add_u64 v[178:179], v[182:183], 0, s[10:11]
	s_mov_b32 m0, s55
	ds_read_b128 v[220:223], v193 offset:54272
	global_load_lds_dwordx4 v[178:179], off
	v_lshl_add_u64 v[178:179], v[184:185], 0, s[10:11]
	s_mov_b32 m0, s56
	ds_read_b128 v[216:219], v193 offset:53248
	global_load_lds_dwordx4 v[178:179], off
	s_waitcnt vmcnt(8)
	s_waitcnt lgkmcnt(0)
	s_setprio 3
	s_barrier
	v_mfma_scale_f32_16x16x128_f8f6f4 v[92:95], v[0:7], v[194:201], v[92:95], v186, v186 op_sel_hi:[0,0,0]
	v_mfma_scale_f32_16x16x128_f8f6f4 v[88:91], v[8:15], v[194:201], v[88:91], v186, v186 op_sel_hi:[0,0,0]
	v_mfma_scale_f32_16x16x128_f8f6f4 v[80:83], v[0:7], v[208:215], v[80:83], v186, v186 op_sel_hi:[0,0,0]
	v_mfma_scale_f32_16x16x128_f8f6f4 v[72:75], v[8:15], v[208:215], v[72:75], v186, v186 op_sel_hi:[0,0,0]
	v_mfma_scale_f32_16x16x128_f8f6f4 v[64:67], v[0:7], v[216:223], v[64:67], v186, v186 op_sel_hi:[0,0,0]
	v_mfma_scale_f32_16x16x128_f8f6f4 v[56:59], v[8:15], v[216:223], v[56:59], v186, v186 op_sel_hi:[0,0,0]
	v_mfma_scale_f32_16x16x128_f8f6f4 v[48:51], v[0:7], v[224:231], v[48:51], v186, v186 op_sel_hi:[0,0,0]
	v_mfma_scale_f32_16x16x128_f8f6f4 v[40:43], v[8:15], v[224:231], v[40:43], v186, v186 op_sel_hi:[0,0,0]
	s_setprio 0
	s_setprio 3
	v_mfma_scale_f32_16x16x128_f8f6f4 v[84:87], v[16:23], v[194:201], v[84:87], v186, v186 op_sel_hi:[0,0,0]
	v_mfma_scale_f32_16x16x128_f8f6f4 v[76:79], v[24:31], v[194:201], v[76:79], v186, v186 op_sel_hi:[0,0,0]
	v_mfma_scale_f32_16x16x128_f8f6f4 v[68:71], v[16:23], v[208:215], v[68:71], v186, v186 op_sel_hi:[0,0,0]
	v_mfma_scale_f32_16x16x128_f8f6f4 v[60:63], v[24:31], v[208:215], v[60:63], v186, v186 op_sel_hi:[0,0,0]
	v_mfma_scale_f32_16x16x128_f8f6f4 v[52:55], v[16:23], v[216:223], v[52:55], v186, v186 op_sel_hi:[0,0,0]
	v_mfma_scale_f32_16x16x128_f8f6f4 v[44:47], v[24:31], v[216:223], v[44:47], v186, v186 op_sel_hi:[0,0,0]
	v_mfma_scale_f32_16x16x128_f8f6f4 v[36:39], v[16:23], v[224:231], v[36:39], v186, v186 op_sel_hi:[0,0,0]
	v_mfma_scale_f32_16x16x128_f8f6f4 v[32:35], v[24:31], v[224:231], v[32:35], v186, v186 op_sel_hi:[0,0,0]
	s_barrier
	s_setprio 0
	s_add_u32 s44, s44, 0x100
	s_addc_u32 s45, s45, 0
	s_add_i32 s70, s70, 2
	s_add_u32 s68, s68, 0x100
	s_addc_u32 s69, s69, 0
	s_cmp_gt_u32 s70, 29
	s_cbranch_scc0 .LBB0_705
	s_and_b64 vcc, exec, s[12:13]
	s_cbranch_vccz .LBB0_708
	s_barrier

.LBB0_1544:
	v_add_u32_e32 v1, s88, v155
	ds_read_b128 v[158:161], v1
	ds_read_b128 v[162:165], v1 offset:1024
	ds_read_b128 v[166:169], v1 offset:2048
	ds_read_b128 v[170:173], v1 offset:3072
	v_add_u32_e32 v1, s89, v155
	s_add_u32 s0, s50, s6
	ds_read_b128 v[174:177], v1
	ds_read_b128 v[178:181], v1 offset:1024
	ds_read_b128 v[182:185], v1 offset:2048
	ds_read_b128 v[186:189], v1 offset:3072
	s_addc_u32 s1, s51, s7
	s_add_u32 s0, s0, 0x100
	s_addc_u32 s1, s1, 0
	s_add_u32 s26, s96, s6
	s_addc_u32 s27, s97, s7
	s_cmpk_eq_i32 s6, 0x1f00
	s_cselect_b32 s55, s47, s1
	s_cselect_b32 s54, s46, s0
	s_cselect_b32 s53, s92, s27
	s_cselect_b32 s52, s93, s26
	v_lshl_add_u64 v[2:3], v[148:149], 0, s[6:7]
	s_add_i32 m0, s61, 0xc000
	ds_read_b128 v[190:193], v157
	ds_read_b128 v[194:197], v157 offset:1024
	ds_read_b128 v[198:201], v157 offset:2048
	ds_read_b128 v[210:213], v157 offset:3072
	ds_read_b128 v[214:217], v157 offset:4096
	ds_read_b128 v[218:221], v157 offset:5120
	ds_read_b128 v[222:225], v157 offset:6144
	global_load_lds_dwordx4 v[2:3], off
	v_lshl_add_u64 v[2:3], v[150:151], 0, s[6:7]
	s_add_i32 m0, s61, 0xe000
	ds_read_b128 v[226:229], v157 offset:7168
	global_load_lds_dwordx4 v[2:3], off
	s_waitcnt vmcnt(8)
	s_waitcnt lgkmcnt(0)
	s_setprio 3
	s_barrier
	v_mfma_f32_16x16x32_bf16 v[128:131], v[158:161], v[190:193], v[128:131]
	v_mfma_f32_16x16x32_bf16 v[124:127], v[166:169], v[190:193], v[124:127]
	v_mfma_f32_16x16x32_bf16 v[112:115], v[158:161], v[198:201], v[112:115]
	v_mfma_f32_16x16x32_bf16 v[108:111], v[166:169], v[198:201], v[108:111]
	v_mfma_f32_16x16x32_bf16 v[96:99], v[158:161], v[214:217], v[96:99]
	v_mfma_f32_16x16x32_bf16 v[92:95], v[166:169], v[214:217], v[92:95]
	v_mfma_f32_16x16x32_bf16 v[80:83], v[158:161], v[222:225], v[80:83]
	v_mfma_f32_16x16x32_bf16 v[76:79], v[166:169], v[222:225], v[76:79]
	v_mfma_f32_16x16x32_bf16 v[128:131], v[162:165], v[194:197], v[128:131]
	v_mfma_f32_16x16x32_bf16 v[124:127], v[170:173], v[194:197], v[124:127]
	v_mfma_f32_16x16x32_bf16 v[112:115], v[162:165], v[210:213], v[112:115]
	v_mfma_f32_16x16x32_bf16 v[108:111], v[170:173], v[210:213], v[108:111]
	v_mfma_f32_16x16x32_bf16 v[96:99], v[162:165], v[218:221], v[96:99]
	v_mfma_f32_16x16x32_bf16 v[92:95], v[170:173], v[218:221], v[92:95]
	v_mfma_f32_16x16x32_bf16 v[80:83], v[162:165], v[226:229], v[80:83]
	v_mfma_f32_16x16x32_bf16 v[76:79], v[170:173], v[226:229], v[76:79]
	s_setprio 0
	s_setprio 3
	v_mfma_f32_16x16x32_bf16 v[120:123], v[174:177], v[190:193], v[120:123]
	v_mfma_f32_16x16x32_bf16 v[116:119], v[182:185], v[190:193], v[116:119]
	v_mfma_f32_16x16x32_bf16 v[104:107], v[174:177], v[198:201], v[104:107]
	v_mfma_f32_16x16x32_bf16 v[100:103], v[182:185], v[198:201], v[100:103]
	v_mfma_f32_16x16x32_bf16 v[88:91], v[174:177], v[214:217], v[88:91]
	v_mfma_f32_16x16x32_bf16 v[84:87], v[182:185], v[214:217], v[84:87]
	v_mfma_f32_16x16x32_bf16 v[72:75], v[174:177], v[222:225], v[72:75]
	v_mfma_f32_16x16x32_bf16 v[68:71], v[182:185], v[222:225], v[68:71]
	v_mfma_f32_16x16x32_bf16 v[120:123], v[178:181], v[194:197], v[120:123]
	v_mfma_f32_16x16x32_bf16 v[116:119], v[186:189], v[194:197], v[116:119]
	v_mfma_f32_16x16x32_bf16 v[104:107], v[178:181], v[210:213], v[104:107]
	v_mfma_f32_16x16x32_bf16 v[100:103], v[186:189], v[210:213], v[100:103]
	v_mfma_f32_16x16x32_bf16 v[88:91], v[178:181], v[218:221], v[88:91]
	v_mfma_f32_16x16x32_bf16 v[84:87], v[186:189], v[218:221], v[84:87]
	v_mfma_f32_16x16x32_bf16 v[72:75], v[178:181], v[226:229], v[72:75]
	v_mfma_f32_16x16x32_bf16 v[68:71], v[186:189], v[226:229], v[68:71]
	s_barrier
	s_setprio 0
	s_add_i32 s0, s88, s60
	v_lshl_add_u64 v[202:203], s[52:53], 0, v[134:135]
	s_mov_b32 m0, s0
	ds_read_b128 v[190:193], v157 offset:16384
	ds_read_b128 v[194:197], v157 offset:17408
	ds_read_b128 v[198:201], v157 offset:18432
	ds_read_b128 v[210:213], v157 offset:19456
	ds_read_b128 v[214:217], v157 offset:20480
	ds_read_b128 v[218:221], v157 offset:21504
	global_load_lds_dwordx4 v[202:203], off
	s_add_i32 m0, s0, 0x2000
	s_add_u32 s0, s52, 0x100000
	v_lshl_add_u64 v[230:231], s[52:53], 0, v[138:139]
	s_addc_u32 s1, s53, 0
	s_add_i32 s26, s89, s60
	global_load_lds_dwordx4 v[230:231], off
	s_mov_b32 m0, s26
	v_lshl_add_u64 v[232:233], s[54:55], 0, v[132:133]
	global_load_lds_dwordx4 v134, s[0:1]
	s_add_i32 m0, s26, 0x2000
	v_lshl_add_u64 v[234:235], s[54:55], 0, v[136:137]
	global_load_lds_dwordx4 v138, s[0:1]
	s_mov_b32 m0, s61
	ds_read_b128 v[226:229], v157 offset:23552
	global_load_lds_dwordx4 v[232:233], off
	s_mov_b32 m0, s62
	ds_read_b128 v[222:225], v157 offset:22528
	global_load_lds_dwordx4 v[234:235], off
	s_waitcnt vmcnt(8)
	s_waitcnt lgkmcnt(0)
	s_setprio 3
	s_barrier
	v_mfma_f32_16x16x32_bf16 v[64:67], v[158:161], v[190:193], v[64:67]
	v_mfma_f32_16x16x32_bf16 v[60:63], v[166:169], v[190:193], v[60:63]
	v_mfma_f32_16x16x32_bf16 v[48:51], v[158:161], v[198:201], v[48:51]
	v_mfma_f32_16x16x32_bf16 v[44:47], v[166:169], v[198:201], v[44:47]
	v_mfma_f32_16x16x32_bf16 v[32:35], v[158:161], v[214:217], v[32:35]
	v_mfma_f32_16x16x32_bf16 v[28:31], v[166:169], v[214:217], v[28:31]
	v_mfma_f32_16x16x32_bf16 v[16:19], v[158:161], v[222:225], v[16:19]
	v_mfma_f32_16x16x32_bf16 v[12:15], v[166:169], v[222:225], v[12:15]
	v_mfma_f32_16x16x32_bf16 v[64:67], v[162:165], v[194:197], v[64:67]
	v_mfma_f32_16x16x32_bf16 v[60:63], v[170:173], v[194:197], v[60:63]
	v_mfma_f32_16x16x32_bf16 v[48:51], v[162:165], v[210:213], v[48:51]
	v_mfma_f32_16x16x32_bf16 v[44:47], v[170:173], v[210:213], v[44:47]
	v_mfma_f32_16x16x32_bf16 v[32:35], v[162:165], v[218:221], v[32:35]
	v_mfma_f32_16x16x32_bf16 v[28:31], v[170:173], v[218:221], v[28:31]
	v_mfma_f32_16x16x32_bf16 v[16:19], v[162:165], v[226:229], v[16:19]
	v_mfma_f32_16x16x32_bf16 v[12:15], v[170:173], v[226:229], v[12:15]
	s_setprio 0
	s_setprio 3
	v_mfma_f32_16x16x32_bf16 v[56:59], v[174:177], v[190:193], v[56:59]
	v_mfma_f32_16x16x32_bf16 v[52:55], v[182:185], v[190:193], v[52:55]
	v_mfma_f32_16x16x32_bf16 v[40:43], v[174:177], v[198:201], v[40:43]
	v_mfma_f32_16x16x32_bf16 v[36:39], v[182:185], v[198:201], v[36:39]
	v_mfma_f32_16x16x32_bf16 v[24:27], v[174:177], v[214:217], v[24:27]
	v_mfma_f32_16x16x32_bf16 v[20:23], v[182:185], v[214:217], v[20:23]
	v_mfma_f32_16x16x32_bf16 v[8:11], v[174:177], v[222:225], v[8:11]
	v_mfma_f32_16x16x32_bf16 v[2:5], v[182:185], v[222:225], v[4:7]
	v_mfma_f32_16x16x32_bf16 v[56:59], v[178:181], v[194:197], v[56:59]
	v_mfma_f32_16x16x32_bf16 v[52:55], v[186:189], v[194:197], v[52:55]
	v_mfma_f32_16x16x32_bf16 v[40:43], v[178:181], v[210:213], v[40:43]
	v_mfma_f32_16x16x32_bf16 v[36:39], v[186:189], v[210:213], v[36:39]
	v_mfma_f32_16x16x32_bf16 v[24:27], v[178:181], v[218:221], v[24:27]
	v_mfma_f32_16x16x32_bf16 v[20:23], v[186:189], v[218:221], v[20:23]
	v_mfma_f32_16x16x32_bf16 v[8:11], v[178:181], v[226:229], v[8:11]
	v_mfma_f32_16x16x32_bf16 v[2:5], v[186:189], v[226:229], v[2:5]
	s_barrier
	s_setprio 0
	s_add_i32 s26, 0, 0x18000
	v_add_u32_e32 v1, s26, v155
	s_add_i32 s27, 0, 0x1c000
	ds_read_b128 v[158:161], v1
	ds_read_b128 v[162:165], v1 offset:1024
	ds_read_b128 v[166:169], v1 offset:2048
	ds_read_b128 v[170:173], v1 offset:3072
	v_add_u32_e32 v1, s27, v155
	ds_read_b128 v[174:177], v1
	ds_read_b128 v[178:181], v1 offset:1024
	ds_read_b128 v[182:185], v1 offset:2048
	ds_read_b128 v[186:189], v1 offset:3072
	s_add_u32 s0, s54, 0x180000
	s_addc_u32 s1, s55, 0
	s_mov_b32 m0, s63
	ds_read_b128 v[190:193], v157 offset:32768
	ds_read_b128 v[194:197], v157 offset:33792
	ds_read_b128 v[198:201], v157 offset:34816
	ds_read_b128 v[210:213], v157 offset:35840
	ds_read_b128 v[214:217], v157 offset:36864
	ds_read_b128 v[218:221], v157 offset:37888
	ds_read_b128 v[222:225], v157 offset:38912
	global_load_lds_dwordx4 v132, s[0:1]
	s_mov_b32 m0, s64
	ds_read_b128 v[226:229], v157 offset:39936
	global_load_lds_dwordx4 v136, s[0:1]
	s_waitcnt vmcnt(8)
	s_waitcnt lgkmcnt(0)
	s_setprio 3
	s_barrier
	v_mfma_f32_16x16x32_bf16 v[128:131], v[158:161], v[190:193], v[128:131]
	v_mfma_f32_16x16x32_bf16 v[124:127], v[166:169], v[190:193], v[124:127]
	v_mfma_f32_16x16x32_bf16 v[112:115], v[158:161], v[198:201], v[112:115]
	v_mfma_f32_16x16x32_bf16 v[108:111], v[166:169], v[198:201], v[108:111]
	v_mfma_f32_16x16x32_bf16 v[96:99], v[158:161], v[214:217], v[96:99]
	v_mfma_f32_16x16x32_bf16 v[92:95], v[166:169], v[214:217], v[92:95]
	v_mfma_f32_16x16x32_bf16 v[80:83], v[158:161], v[222:225], v[80:83]
	v_mfma_f32_16x16x32_bf16 v[76:79], v[166:169], v[222:225], v[76:79]
	v_mfma_f32_16x16x32_bf16 v[128:131], v[162:165], v[194:197], v[128:131]
	v_mfma_f32_16x16x32_bf16 v[124:127], v[170:173], v[194:197], v[124:127]
	v_mfma_f32_16x16x32_bf16 v[112:115], v[162:165], v[210:213], v[112:115]
	v_mfma_f32_16x16x32_bf16 v[108:111], v[170:173], v[210:213], v[108:111]
	v_mfma_f32_16x16x32_bf16 v[96:99], v[162:165], v[218:221], v[96:99]
	v_mfma_f32_16x16x32_bf16 v[92:95], v[170:173], v[218:221], v[92:95]
	v_mfma_f32_16x16x32_bf16 v[80:83], v[162:165], v[226:229], v[80:83]
	v_mfma_f32_16x16x32_bf16 v[76:79], v[170:173], v[226:229], v[76:79]
	s_setprio 0
	s_setprio 3
	v_mfma_f32_16x16x32_bf16 v[120:123], v[174:177], v[190:193], v[120:123]
	v_mfma_f32_16x16x32_bf16 v[116:119], v[182:185], v[190:193], v[116:119]
	v_mfma_f32_16x16x32_bf16 v[104:107], v[174:177], v[198:201], v[104:107]
	v_mfma_f32_16x16x32_bf16 v[100:103], v[182:185], v[198:201], v[100:103]
	v_mfma_f32_16x16x32_bf16 v[88:91], v[174:177], v[214:217], v[88:91]
	v_mfma_f32_16x16x32_bf16 v[84:87], v[182:185], v[214:217], v[84:87]
	v_mfma_f32_16x16x32_bf16 v[72:75], v[174:177], v[222:225], v[72:75]
	v_mfma_f32_16x16x32_bf16 v[68:71], v[182:185], v[222:225], v[68:71]
	v_mfma_f32_16x16x32_bf16 v[120:123], v[178:181], v[194:197], v[120:123]
	v_mfma_f32_16x16x32_bf16 v[116:119], v[186:189], v[194:197], v[116:119]
	v_mfma_f32_16x16x32_bf16 v[104:107], v[178:181], v[210:213], v[104:107]
	v_mfma_f32_16x16x32_bf16 v[100:103], v[186:189], v[210:213], v[100:103]
	v_mfma_f32_16x16x32_bf16 v[88:91], v[178:181], v[218:221], v[88:91]
	v_mfma_f32_16x16x32_bf16 v[84:87], v[186:189], v[218:221], v[84:87]
	v_mfma_f32_16x16x32_bf16 v[72:75], v[178:181], v[226:229], v[72:75]
	v_mfma_f32_16x16x32_bf16 v[68:71], v[186:189], v[226:229], v[68:71]
	s_barrier
	s_setprio 0
	s_add_i32 s0, s26, s60
	v_lshl_add_u64 v[6:7], v[202:203], 0, s[16:17]
	s_mov_b32 m0, s0
	ds_read_b128 v[190:193], v157 offset:49152
	ds_read_b128 v[194:197], v157 offset:50176
	ds_read_b128 v[198:201], v157 offset:51200
	ds_read_b128 v[210:213], v157 offset:52224
	global_load_lds_dwordx4 v[6:7], off
	s_add_i32 m0, s0, 0x2000
	s_add_u32 s0, s52, 0x100080
	v_lshl_add_u64 v[6:7], v[230:231], 0, s[16:17]
	s_addc_u32 s1, s53, 0
	s_add_i32 s26, s27, s60
	global_load_lds_dwordx4 v[6:7], off
	s_mov_b32 m0, s26
	ds_read_b128 v[226:229], v157 offset:56320
	global_load_lds_dwordx4 v134, s[0:1]
	s_add_i32 m0, s26, 0x2000
	ds_read_b128 v[222:225], v157 offset:55296
	global_load_lds_dwordx4 v138, s[0:1]
	v_lshl_add_u64 v[6:7], v[232:233], 0, s[16:17]
	s_mov_b32 m0, s68
	ds_read_b128 v[218:221], v157 offset:54272
	global_load_lds_dwordx4 v[6:7], off
	v_lshl_add_u64 v[6:7], v[234:235], 0, s[16:17]
	s_mov_b32 m0, s69
	ds_read_b128 v[214:217], v157 offset:53248
	global_load_lds_dwordx4 v[6:7], off
	s_waitcnt vmcnt(8)
	s_waitcnt lgkmcnt(0)
	s_setprio 3
	s_barrier
	v_mfma_f32_16x16x32_bf16 v[64:67], v[158:161], v[190:193], v[64:67]
	v_mfma_f32_16x16x32_bf16 v[60:63], v[166:169], v[190:193], v[60:63]
	v_mfma_f32_16x16x32_bf16 v[48:51], v[158:161], v[198:201], v[48:51]
	v_mfma_f32_16x16x32_bf16 v[44:47], v[166:169], v[198:201], v[44:47]
	v_mfma_f32_16x16x32_bf16 v[32:35], v[158:161], v[214:217], v[32:35]
	v_mfma_f32_16x16x32_bf16 v[28:31], v[166:169], v[214:217], v[28:31]
	v_mfma_f32_16x16x32_bf16 v[16:19], v[158:161], v[222:225], v[16:19]
	v_mfma_f32_16x16x32_bf16 v[12:15], v[166:169], v[222:225], v[12:15]
	v_mfma_f32_16x16x32_bf16 v[64:67], v[162:165], v[194:197], v[64:67]
	v_mfma_f32_16x16x32_bf16 v[60:63], v[170:173], v[194:197], v[60:63]
	v_mfma_f32_16x16x32_bf16 v[48:51], v[162:165], v[210:213], v[48:51]
	v_mfma_f32_16x16x32_bf16 v[44:47], v[170:173], v[210:213], v[44:47]
	v_mfma_f32_16x16x32_bf16 v[32:35], v[162:165], v[218:221], v[32:35]
	v_mfma_f32_16x16x32_bf16 v[28:31], v[170:173], v[218:221], v[28:31]
	v_mfma_f32_16x16x32_bf16 v[16:19], v[162:165], v[226:229], v[16:19]
	v_mfma_f32_16x16x32_bf16 v[12:15], v[170:173], v[226:229], v[12:15]
	s_setprio 0
	s_setprio 3
	v_mfma_f32_16x16x32_bf16 v[56:59], v[174:177], v[190:193], v[56:59]
	v_mfma_f32_16x16x32_bf16 v[52:55], v[182:185], v[190:193], v[52:55]
	v_mfma_f32_16x16x32_bf16 v[40:43], v[174:177], v[198:201], v[40:43]
	v_mfma_f32_16x16x32_bf16 v[36:39], v[182:185], v[198:201], v[36:39]
	v_mfma_f32_16x16x32_bf16 v[24:27], v[174:177], v[214:217], v[24:27]
	v_mfma_f32_16x16x32_bf16 v[20:23], v[182:185], v[214:217], v[20:23]
	v_mfma_f32_16x16x32_bf16 v[6:9], v[174:177], v[222:225], v[8:11]
	v_mfma_f32_16x16x32_bf16 v[2:5], v[182:185], v[222:225], v[2:5]
	v_mfma_f32_16x16x32_bf16 v[56:59], v[178:181], v[194:197], v[56:59]
	v_mfma_f32_16x16x32_bf16 v[52:55], v[186:189], v[194:197], v[52:55]
	v_mfma_f32_16x16x32_bf16 v[40:43], v[178:181], v[210:213], v[40:43]
	v_mfma_f32_16x16x32_bf16 v[36:39], v[186:189], v[210:213], v[36:39]
	v_mfma_f32_16x16x32_bf16 v[24:27], v[178:181], v[218:221], v[24:27]
	v_mfma_f32_16x16x32_bf16 v[20:23], v[186:189], v[218:221], v[20:23]
	v_mfma_f32_16x16x32_bf16 v[8:11], v[178:181], v[226:229], v[6:9]
	v_mfma_f32_16x16x32_bf16 v[4:7], v[186:189], v[226:229], v[2:5]
	s_barrier
	s_setprio 0
	s_add_u32 s6, s6, 0x100
	s_addc_u32 s7, s7, 0
	s_add_i32 s23, s23, 2
	s_cmp_gt_u32 s23, 61
	s_cbranch_scc1 .LBB0_1547

.LBB0_1637:
	ds_read_b128 v[152:155], v149
	ds_read_b128 v[156:159], v149 offset:1024
	ds_read_b128 v[160:163], v149 offset:2048
	ds_read_b128 v[164:167], v149 offset:3072
	ds_read_b128 v[168:171], v150
	ds_read_b128 v[172:175], v150 offset:1024
	ds_read_b128 v[176:179], v150 offset:2048
	ds_read_b128 v[180:183], v150 offset:3072
	s_add_u32 s0, s42, 0xfff00080
	s_addc_u32 s1, s43, -1
	s_cmp_eq_u32 s68, 60
	s_cselect_b32 s47, s35, s1
	s_cselect_b32 s46, s64, s0
	s_cselect_b32 s45, s31, s67
	s_cselect_b32 s44, s65, s66
	s_add_i32 m0, s41, 0xc000
	ds_read_b128 v[184:187], v151
	ds_read_b128 v[188:191], v151 offset:1024
	ds_read_b128 v[192:195], v151 offset:2048
	ds_read_b128 v[196:199], v151 offset:3072
	ds_read_b128 v[200:203], v151 offset:4096
	ds_read_b128 v[210:213], v151 offset:5120
	ds_read_b128 v[214:217], v151 offset:6144
	global_load_lds_dwordx4 v136, s[42:43]
	s_add_i32 m0, s41, 0xe000
	ds_read_b128 v[218:221], v151 offset:7168
	global_load_lds_dwordx4 v138, s[42:43]
	s_waitcnt vmcnt(8)
	s_waitcnt lgkmcnt(0)
	s_setprio 3
	s_barrier
	v_mfma_f32_16x16x32_bf16 v[124:127], v[152:155], v[184:187], v[124:127]
	v_mfma_f32_16x16x32_bf16 v[120:123], v[160:163], v[184:187], v[120:123]
	v_mfma_f32_16x16x32_bf16 v[116:119], v[152:155], v[192:195], v[116:119]
	v_mfma_f32_16x16x32_bf16 v[108:111], v[160:163], v[192:195], v[108:111]
	v_mfma_f32_16x16x32_bf16 v[100:103], v[152:155], v[200:203], v[100:103]
	v_mfma_f32_16x16x32_bf16 v[92:95], v[160:163], v[200:203], v[92:95]
	v_mfma_f32_16x16x32_bf16 v[84:87], v[152:155], v[214:217], v[84:87]
	v_mfma_f32_16x16x32_bf16 v[76:79], v[160:163], v[214:217], v[76:79]
	v_mfma_f32_16x16x32_bf16 v[124:127], v[156:159], v[188:191], v[124:127]
	v_mfma_f32_16x16x32_bf16 v[120:123], v[164:167], v[188:191], v[120:123]
	v_mfma_f32_16x16x32_bf16 v[116:119], v[156:159], v[196:199], v[116:119]
	v_mfma_f32_16x16x32_bf16 v[108:111], v[164:167], v[196:199], v[108:111]
	v_mfma_f32_16x16x32_bf16 v[100:103], v[156:159], v[210:213], v[100:103]
	v_mfma_f32_16x16x32_bf16 v[92:95], v[164:167], v[210:213], v[92:95]
	v_mfma_f32_16x16x32_bf16 v[84:87], v[156:159], v[218:221], v[84:87]
	v_mfma_f32_16x16x32_bf16 v[76:79], v[164:167], v[218:221], v[76:79]
	s_setprio 0
	s_setprio 3
	v_mfma_f32_16x16x32_bf16 v[112:115], v[168:171], v[184:187], v[112:115]
	v_mfma_f32_16x16x32_bf16 v[104:107], v[176:179], v[184:187], v[104:107]
	v_mfma_f32_16x16x32_bf16 v[96:99], v[168:171], v[192:195], v[96:99]
	v_mfma_f32_16x16x32_bf16 v[88:91], v[176:179], v[192:195], v[88:91]
	v_mfma_f32_16x16x32_bf16 v[80:83], v[168:171], v[200:203], v[80:83]
	v_mfma_f32_16x16x32_bf16 v[72:75], v[176:179], v[200:203], v[72:75]
	v_mfma_f32_16x16x32_bf16 v[68:71], v[168:171], v[214:217], v[68:71]
	v_mfma_f32_16x16x32_bf16 v[64:67], v[176:179], v[214:217], v[64:67]
	v_mfma_f32_16x16x32_bf16 v[112:115], v[172:175], v[188:191], v[112:115]
	v_mfma_f32_16x16x32_bf16 v[104:107], v[180:183], v[188:191], v[104:107]
	v_mfma_f32_16x16x32_bf16 v[96:99], v[172:175], v[196:199], v[96:99]
	v_mfma_f32_16x16x32_bf16 v[88:91], v[180:183], v[196:199], v[88:91]
	v_mfma_f32_16x16x32_bf16 v[80:83], v[172:175], v[210:213], v[80:83]
	v_mfma_f32_16x16x32_bf16 v[72:75], v[180:183], v[210:213], v[72:75]
	v_mfma_f32_16x16x32_bf16 v[68:71], v[172:175], v[218:221], v[68:71]
	v_mfma_f32_16x16x32_bf16 v[64:67], v[180:183], v[218:221], v[64:67]
	s_barrier
	s_setprio 0
	s_add_i32 s0, s57, s49
	v_lshl_add_u64 v[144:145], s[44:45], 0, v[130:131]
	s_mov_b32 m0, s0
	ds_read_b128 v[184:187], v151 offset:16384
	ds_read_b128 v[188:191], v151 offset:17408
	ds_read_b128 v[192:195], v151 offset:18432
	ds_read_b128 v[196:199], v151 offset:19456
	ds_read_b128 v[200:203], v151 offset:20480
	global_load_lds_dwordx4 v[144:145], off
	s_add_i32 m0, s0, 0x2000
	s_add_u32 s0, s44, 0x100000
	v_lshl_add_u64 v[222:223], s[44:45], 0, v[134:135]
	s_addc_u32 s1, s45, 0
	s_add_i32 s69, s58, s49
	global_load_lds_dwordx4 v[222:223], off
	s_mov_b32 m0, s69
	v_lshl_add_u64 v[226:227], s[46:47], 0, v[132:133]
	global_load_lds_dwordx4 v130, s[0:1]
	s_add_i32 m0, s69, 0x2000
	ds_read_b128 v[218:221], v151 offset:23552
	global_load_lds_dwordx4 v134, s[0:1]
	v_lshl_add_u64 v[224:225], s[46:47], 0, v[128:129]
	s_mov_b32 m0, s41
	ds_read_b128 v[214:217], v151 offset:22528
	global_load_lds_dwordx4 v[224:225], off
	s_mov_b32 m0, s50
	ds_read_b128 v[210:213], v151 offset:21504
	global_load_lds_dwordx4 v[226:227], off
	s_waitcnt vmcnt(8)
	s_waitcnt lgkmcnt(0)
	s_setprio 3
	s_barrier
	v_mfma_f32_16x16x32_bf16 v[60:63], v[152:155], v[184:187], v[60:63]
	v_mfma_f32_16x16x32_bf16 v[56:59], v[160:163], v[184:187], v[56:59]
	v_mfma_f32_16x16x32_bf16 v[52:55], v[152:155], v[192:195], v[52:55]
	v_mfma_f32_16x16x32_bf16 v[44:47], v[160:163], v[192:195], v[44:47]
	v_mfma_f32_16x16x32_bf16 v[36:39], v[152:155], v[200:203], v[36:39]
	v_mfma_f32_16x16x32_bf16 v[28:31], v[160:163], v[200:203], v[28:31]
	v_mfma_f32_16x16x32_bf16 v[20:23], v[152:155], v[214:217], v[20:23]
	v_mfma_f32_16x16x32_bf16 v[12:15], v[160:163], v[214:217], v[12:15]
	v_mfma_f32_16x16x32_bf16 v[60:63], v[156:159], v[188:191], v[60:63]
	v_mfma_f32_16x16x32_bf16 v[56:59], v[164:167], v[188:191], v[56:59]
	v_mfma_f32_16x16x32_bf16 v[52:55], v[156:159], v[196:199], v[52:55]
	v_mfma_f32_16x16x32_bf16 v[44:47], v[164:167], v[196:199], v[44:47]
	v_mfma_f32_16x16x32_bf16 v[36:39], v[156:159], v[210:213], v[36:39]
	v_mfma_f32_16x16x32_bf16 v[28:31], v[164:167], v[210:213], v[28:31]
	v_mfma_f32_16x16x32_bf16 v[20:23], v[156:159], v[218:221], v[20:23]
	v_mfma_f32_16x16x32_bf16 v[12:15], v[164:167], v[218:221], v[12:15]
	s_setprio 0
	s_setprio 3
	v_mfma_f32_16x16x32_bf16 v[48:51], v[168:171], v[184:187], v[48:51]
	v_mfma_f32_16x16x32_bf16 v[40:43], v[176:179], v[184:187], v[40:43]
	v_mfma_f32_16x16x32_bf16 v[32:35], v[168:171], v[192:195], v[32:35]
	v_mfma_f32_16x16x32_bf16 v[24:27], v[176:179], v[192:195], v[24:27]
	v_mfma_f32_16x16x32_bf16 v[16:19], v[168:171], v[200:203], v[16:19]
	v_mfma_f32_16x16x32_bf16 v[8:11], v[176:179], v[200:203], v[8:11]
	v_mfma_f32_16x16x32_bf16 v[4:7], v[168:171], v[214:217], v[4:7]
	v_mfma_f32_16x16x32_bf16 v[0:3], v[176:179], v[214:217], v[0:3]
	v_mfma_f32_16x16x32_bf16 v[48:51], v[172:175], v[188:191], v[48:51]
	v_mfma_f32_16x16x32_bf16 v[40:43], v[180:183], v[188:191], v[40:43]
	v_mfma_f32_16x16x32_bf16 v[32:35], v[172:175], v[196:199], v[32:35]
	v_mfma_f32_16x16x32_bf16 v[24:27], v[180:183], v[196:199], v[24:27]
	v_mfma_f32_16x16x32_bf16 v[16:19], v[172:175], v[210:213], v[16:19]
	v_mfma_f32_16x16x32_bf16 v[8:11], v[180:183], v[210:213], v[8:11]
	v_mfma_f32_16x16x32_bf16 v[4:7], v[172:175], v[218:221], v[4:7]
	v_mfma_f32_16x16x32_bf16 v[0:3], v[180:183], v[218:221], v[0:3]
	s_barrier
	s_setprio 0
	s_add_i32 s69, 0, 0x18000
	s_add_i32 s70, 0, 0x1c000
	v_add_u32_e32 v164, s69, v147
	v_add_u32_e32 v180, s70, v147
	ds_read_b128 v[152:155], v164
	ds_read_b128 v[156:159], v164 offset:1024
	ds_read_b128 v[160:163], v164 offset:2048
	ds_read_b128 v[164:167], v164 offset:3072
	ds_read_b128 v[168:171], v180
	ds_read_b128 v[172:175], v180 offset:1024
	ds_read_b128 v[176:179], v180 offset:2048
	ds_read_b128 v[180:183], v180 offset:3072
	s_add_u32 s0, s46, 0x100000
	s_addc_u32 s1, s47, 0
	s_mov_b32 m0, s51
	ds_read_b128 v[184:187], v151 offset:32768
	ds_read_b128 v[188:191], v151 offset:33792
	ds_read_b128 v[192:195], v151 offset:34816
	ds_read_b128 v[196:199], v151 offset:35840
	ds_read_b128 v[200:203], v151 offset:36864
	ds_read_b128 v[210:213], v151 offset:37888
	ds_read_b128 v[214:217], v151 offset:38912
	global_load_lds_dwordx4 v128, s[0:1]
	s_mov_b32 m0, s52
	ds_read_b128 v[218:221], v151 offset:39936
	global_load_lds_dwordx4 v132, s[0:1]
	s_waitcnt vmcnt(8)
	s_waitcnt lgkmcnt(0)
	s_setprio 3
	s_barrier
	v_mfma_f32_16x16x32_bf16 v[124:127], v[152:155], v[184:187], v[124:127]
	v_mfma_f32_16x16x32_bf16 v[120:123], v[160:163], v[184:187], v[120:123]
	v_mfma_f32_16x16x32_bf16 v[116:119], v[152:155], v[192:195], v[116:119]
	v_mfma_f32_16x16x32_bf16 v[108:111], v[160:163], v[192:195], v[108:111]
	v_mfma_f32_16x16x32_bf16 v[100:103], v[152:155], v[200:203], v[100:103]
	v_mfma_f32_16x16x32_bf16 v[92:95], v[160:163], v[200:203], v[92:95]
	v_mfma_f32_16x16x32_bf16 v[84:87], v[152:155], v[214:217], v[84:87]
	v_mfma_f32_16x16x32_bf16 v[76:79], v[160:163], v[214:217], v[76:79]
	v_mfma_f32_16x16x32_bf16 v[124:127], v[156:159], v[188:191], v[124:127]
	v_mfma_f32_16x16x32_bf16 v[120:123], v[164:167], v[188:191], v[120:123]
	v_mfma_f32_16x16x32_bf16 v[116:119], v[156:159], v[196:199], v[116:119]
	v_mfma_f32_16x16x32_bf16 v[108:111], v[164:167], v[196:199], v[108:111]
	v_mfma_f32_16x16x32_bf16 v[100:103], v[156:159], v[210:213], v[100:103]
	v_mfma_f32_16x16x32_bf16 v[92:95], v[164:167], v[210:213], v[92:95]
	v_mfma_f32_16x16x32_bf16 v[84:87], v[156:159], v[218:221], v[84:87]
	v_mfma_f32_16x16x32_bf16 v[76:79], v[164:167], v[218:221], v[76:79]
	s_setprio 0
	s_setprio 3
	v_mfma_f32_16x16x32_bf16 v[112:115], v[168:171], v[184:187], v[112:115]
	v_mfma_f32_16x16x32_bf16 v[104:107], v[176:179], v[184:187], v[104:107]
	v_mfma_f32_16x16x32_bf16 v[96:99], v[168:171], v[192:195], v[96:99]
	v_mfma_f32_16x16x32_bf16 v[88:91], v[176:179], v[192:195], v[88:91]
	v_mfma_f32_16x16x32_bf16 v[80:83], v[168:171], v[200:203], v[80:83]
	v_mfma_f32_16x16x32_bf16 v[72:75], v[176:179], v[200:203], v[72:75]
	v_mfma_f32_16x16x32_bf16 v[68:71], v[168:171], v[214:217], v[68:71]
	v_mfma_f32_16x16x32_bf16 v[64:67], v[176:179], v[214:217], v[64:67]
	v_mfma_f32_16x16x32_bf16 v[112:115], v[172:175], v[188:191], v[112:115]
	v_mfma_f32_16x16x32_bf16 v[104:107], v[180:183], v[188:191], v[104:107]
	v_mfma_f32_16x16x32_bf16 v[96:99], v[172:175], v[196:199], v[96:99]
	v_mfma_f32_16x16x32_bf16 v[88:91], v[180:183], v[196:199], v[88:91]
	v_mfma_f32_16x16x32_bf16 v[80:83], v[172:175], v[210:213], v[80:83]
	v_mfma_f32_16x16x32_bf16 v[72:75], v[180:183], v[210:213], v[72:75]
	v_mfma_f32_16x16x32_bf16 v[68:71], v[172:175], v[218:221], v[68:71]
	v_mfma_f32_16x16x32_bf16 v[64:67], v[180:183], v[218:221], v[64:67]
	s_barrier
	s_setprio 0
	s_add_i32 s0, s69, s49
	v_lshl_add_u64 v[144:145], v[144:145], 0, s[14:15]
	s_mov_b32 m0, s0
	ds_read_b128 v[184:187], v151 offset:49152
	ds_read_b128 v[188:191], v151 offset:50176
	ds_read_b128 v[192:195], v151 offset:51200
	ds_read_b128 v[196:199], v151 offset:52224
	global_load_lds_dwordx4 v[144:145], off
	s_add_i32 m0, s0, 0x2000
	s_add_u32 s0, s44, 0x100080
	v_lshl_add_u64 v[144:145], v[222:223], 0, s[14:15]
	s_addc_u32 s1, s45, 0
	s_add_i32 s44, s70, s49
	global_load_lds_dwordx4 v[144:145], off
	s_mov_b32 m0, s44
	ds_read_b128 v[218:221], v151 offset:56320
	global_load_lds_dwordx4 v130, s[0:1]
	s_add_i32 m0, s44, 0x2000
	ds_read_b128 v[214:217], v151 offset:55296
	global_load_lds_dwordx4 v134, s[0:1]
	v_lshl_add_u64 v[144:145], v[224:225], 0, s[14:15]
	s_mov_b32 m0, s54
	ds_read_b128 v[210:213], v151 offset:54272
	global_load_lds_dwordx4 v[144:145], off
	v_lshl_add_u64 v[144:145], v[226:227], 0, s[14:15]
	s_mov_b32 m0, s55
	ds_read_b128 v[200:203], v151 offset:53248
	global_load_lds_dwordx4 v[144:145], off
	s_waitcnt vmcnt(8)
	s_waitcnt lgkmcnt(0)
	s_setprio 3
	s_barrier
	v_mfma_f32_16x16x32_bf16 v[60:63], v[152:155], v[184:187], v[60:63]
	v_mfma_f32_16x16x32_bf16 v[56:59], v[160:163], v[184:187], v[56:59]
	v_mfma_f32_16x16x32_bf16 v[52:55], v[152:155], v[192:195], v[52:55]
	v_mfma_f32_16x16x32_bf16 v[44:47], v[160:163], v[192:195], v[44:47]
	v_mfma_f32_16x16x32_bf16 v[36:39], v[152:155], v[200:203], v[36:39]
	v_mfma_f32_16x16x32_bf16 v[28:31], v[160:163], v[200:203], v[28:31]
	v_mfma_f32_16x16x32_bf16 v[20:23], v[152:155], v[214:217], v[20:23]
	v_mfma_f32_16x16x32_bf16 v[12:15], v[160:163], v[214:217], v[12:15]
	v_mfma_f32_16x16x32_bf16 v[60:63], v[156:159], v[188:191], v[60:63]
	v_mfma_f32_16x16x32_bf16 v[56:59], v[164:167], v[188:191], v[56:59]
	v_mfma_f32_16x16x32_bf16 v[52:55], v[156:159], v[196:199], v[52:55]
	v_mfma_f32_16x16x32_bf16 v[44:47], v[164:167], v[196:199], v[44:47]
	v_mfma_f32_16x16x32_bf16 v[36:39], v[156:159], v[210:213], v[36:39]
	v_mfma_f32_16x16x32_bf16 v[28:31], v[164:167], v[210:213], v[28:31]
	v_mfma_f32_16x16x32_bf16 v[20:23], v[156:159], v[218:221], v[20:23]
	v_mfma_f32_16x16x32_bf16 v[12:15], v[164:167], v[218:221], v[12:15]
	s_setprio 0
	s_setprio 3
	v_mfma_f32_16x16x32_bf16 v[48:51], v[168:171], v[184:187], v[48:51]
	v_mfma_f32_16x16x32_bf16 v[40:43], v[176:179], v[184:187], v[40:43]
	v_mfma_f32_16x16x32_bf16 v[32:35], v[168:171], v[192:195], v[32:35]
	v_mfma_f32_16x16x32_bf16 v[24:27], v[176:179], v[192:195], v[24:27]
	v_mfma_f32_16x16x32_bf16 v[16:19], v[168:171], v[200:203], v[16:19]
	v_mfma_f32_16x16x32_bf16 v[8:11], v[176:179], v[200:203], v[8:11]
	v_mfma_f32_16x16x32_bf16 v[4:7], v[168:171], v[214:217], v[4:7]
	v_mfma_f32_16x16x32_bf16 v[0:3], v[176:179], v[214:217], v[0:3]
	v_mfma_f32_16x16x32_bf16 v[48:51], v[172:175], v[188:191], v[48:51]
	v_mfma_f32_16x16x32_bf16 v[40:43], v[180:183], v[188:191], v[40:43]
	v_mfma_f32_16x16x32_bf16 v[32:35], v[172:175], v[196:199], v[32:35]
	v_mfma_f32_16x16x32_bf16 v[24:27], v[180:183], v[196:199], v[24:27]
	v_mfma_f32_16x16x32_bf16 v[16:19], v[172:175], v[210:213], v[16:19]
	v_mfma_f32_16x16x32_bf16 v[8:11], v[180:183], v[210:213], v[8:11]
	v_mfma_f32_16x16x32_bf16 v[4:7], v[172:175], v[218:221], v[4:7]
	v_mfma_f32_16x16x32_bf16 v[0:3], v[180:183], v[218:221], v[0:3]
	s_barrier
	s_setprio 0
	s_add_u32 s42, s42, 0x100
	s_addc_u32 s43, s43, 0
	s_add_i32 s68, s68, 2
	s_add_u32 s66, s66, 0x100
	s_addc_u32 s67, s67, 0
	s_cmp_gt_u32 s68, 61
	s_cbranch_scc0 .LBB0_1637
	s_and_b64 vcc, exec, s[16:17]
	s_cbranch_vccz .LBB0_1640
	s_barrier

.LBB0_1813:
	ds_read_b128 v[148:151], v156
	ds_read_b128 v[160:163], v156 offset:1024
	ds_read_b128 v[164:167], v156 offset:2048
	ds_read_b128 v[168:171], v156 offset:3072
	ds_read_b128 v[172:175], v157
	ds_read_b128 v[176:179], v157 offset:1024
	ds_read_b128 v[180:183], v157 offset:2048
	ds_read_b128 v[184:187], v157 offset:3072
	s_add_u32 s0, s36, 0xfff00080
	s_addc_u32 s1, s37, -1
	s_cmp_eq_u32 s64, 60
	s_cselect_b32 s41, s59, s1
	s_cselect_b32 s40, s60, s0
	s_cselect_b32 s39, s17, s63
	s_cselect_b32 s38, s61, s62
	s_add_i32 m0, s31, 0xc000
	ds_read_b128 v[188:191], v158
	ds_read_b128 v[192:195], v158 offset:1024
	ds_read_b128 v[196:199], v158 offset:2048
	ds_read_b128 v[200:203], v158 offset:3072
	ds_read_b128 v[210:213], v158 offset:4096
	ds_read_b128 v[214:217], v158 offset:5120
	ds_read_b128 v[218:221], v158 offset:6144
	global_load_lds_dwordx4 v140, s[36:37]
	s_add_i32 m0, s31, 0xe000
	ds_read_b128 v[222:225], v158 offset:7168
	global_load_lds_dwordx4 v142, s[36:37]
	s_waitcnt vmcnt(8)
	s_waitcnt lgkmcnt(0)
	s_setprio 3
	s_barrier
	v_mfma_f32_16x16x32_bf16 v[124:127], v[148:151], v[188:191], v[124:127]
	v_mfma_f32_16x16x32_bf16 v[120:123], v[164:167], v[188:191], v[120:123]
	v_mfma_f32_16x16x32_bf16 v[108:111], v[148:151], v[196:199], v[108:111]
	v_mfma_f32_16x16x32_bf16 v[104:107], v[164:167], v[196:199], v[104:107]
	v_mfma_f32_16x16x32_bf16 v[92:95], v[148:151], v[210:213], v[92:95]
	v_mfma_f32_16x16x32_bf16 v[88:91], v[164:167], v[210:213], v[88:91]
	v_mfma_f32_16x16x32_bf16 v[76:79], v[148:151], v[218:221], v[76:79]
	v_mfma_f32_16x16x32_bf16 v[72:75], v[164:167], v[218:221], v[72:75]
	v_mfma_f32_16x16x32_bf16 v[124:127], v[160:163], v[192:195], v[124:127]
	v_mfma_f32_16x16x32_bf16 v[120:123], v[168:171], v[192:195], v[120:123]
	v_mfma_f32_16x16x32_bf16 v[108:111], v[160:163], v[200:203], v[108:111]
	v_mfma_f32_16x16x32_bf16 v[104:107], v[168:171], v[200:203], v[104:107]
	v_mfma_f32_16x16x32_bf16 v[92:95], v[160:163], v[214:217], v[92:95]
	v_mfma_f32_16x16x32_bf16 v[88:91], v[168:171], v[214:217], v[88:91]
	v_mfma_f32_16x16x32_bf16 v[76:79], v[160:163], v[222:225], v[76:79]
	v_mfma_f32_16x16x32_bf16 v[72:75], v[168:171], v[222:225], v[72:75]
	s_setprio 0
	s_setprio 3
	v_mfma_f32_16x16x32_bf16 v[116:119], v[172:175], v[188:191], v[116:119]
	v_mfma_f32_16x16x32_bf16 v[112:115], v[180:183], v[188:191], v[112:115]
	v_mfma_f32_16x16x32_bf16 v[100:103], v[172:175], v[196:199], v[100:103]
	v_mfma_f32_16x16x32_bf16 v[96:99], v[180:183], v[196:199], v[96:99]
	v_mfma_f32_16x16x32_bf16 v[84:87], v[172:175], v[210:213], v[84:87]
	v_mfma_f32_16x16x32_bf16 v[80:83], v[180:183], v[210:213], v[80:83]
	v_mfma_f32_16x16x32_bf16 v[68:71], v[172:175], v[218:221], v[68:71]
	v_mfma_f32_16x16x32_bf16 v[64:67], v[180:183], v[218:221], v[64:67]
	v_mfma_f32_16x16x32_bf16 v[116:119], v[176:179], v[192:195], v[116:119]
	v_mfma_f32_16x16x32_bf16 v[112:115], v[184:187], v[192:195], v[112:115]
	v_mfma_f32_16x16x32_bf16 v[100:103], v[176:179], v[200:203], v[100:103]
	v_mfma_f32_16x16x32_bf16 v[96:99], v[184:187], v[200:203], v[96:99]
	v_mfma_f32_16x16x32_bf16 v[84:87], v[176:179], v[214:217], v[84:87]
	v_mfma_f32_16x16x32_bf16 v[80:83], v[184:187], v[214:217], v[80:83]
	v_mfma_f32_16x16x32_bf16 v[68:71], v[176:179], v[222:225], v[68:71]
	v_mfma_f32_16x16x32_bf16 v[64:67], v[184:187], v[222:225], v[64:67]
	s_barrier
	s_setprio 0
	s_add_i32 s0, s52, s43
	v_lshl_add_u64 v[226:227], s[38:39], 0, v[132:133]
	s_mov_b32 m0, s0
	ds_read_b128 v[188:191], v158 offset:16384
	ds_read_b128 v[192:195], v158 offset:17408
	ds_read_b128 v[196:199], v158 offset:18432
	ds_read_b128 v[200:203], v158 offset:19456
	ds_read_b128 v[210:213], v158 offset:20480
	global_load_lds_dwordx4 v[226:227], off
	s_add_i32 m0, s0, 0x2000
	s_add_u32 s0, s38, 0x100000
	v_lshl_add_u64 v[228:229], s[38:39], 0, v[136:137]
	s_addc_u32 s1, s39, 0
	s_add_i32 s65, s53, s43
	global_load_lds_dwordx4 v[228:229], off
	s_mov_b32 m0, s65
	v_lshl_add_u64 v[232:233], s[40:41], 0, v[134:135]
	global_load_lds_dwordx4 v132, s[0:1]
	s_add_i32 m0, s65, 0x2000
	ds_read_b128 v[222:225], v158 offset:23552
	global_load_lds_dwordx4 v136, s[0:1]
	v_lshl_add_u64 v[230:231], s[40:41], 0, v[130:131]
	s_mov_b32 m0, s31
	ds_read_b128 v[218:221], v158 offset:22528
	global_load_lds_dwordx4 v[230:231], off
	s_mov_b32 m0, s35
	ds_read_b128 v[214:217], v158 offset:21504
	global_load_lds_dwordx4 v[232:233], off
	s_waitcnt vmcnt(8)
	s_waitcnt lgkmcnt(0)
	s_setprio 3
	s_barrier
	v_mfma_f32_16x16x32_bf16 v[60:63], v[148:151], v[188:191], v[60:63]
	v_mfma_f32_16x16x32_bf16 v[56:59], v[164:167], v[188:191], v[56:59]
	v_mfma_f32_16x16x32_bf16 v[44:47], v[148:151], v[196:199], v[44:47]
	v_mfma_f32_16x16x32_bf16 v[40:43], v[164:167], v[196:199], v[40:43]
	v_mfma_f32_16x16x32_bf16 v[28:31], v[148:151], v[210:213], v[28:31]
	v_mfma_f32_16x16x32_bf16 v[24:27], v[164:167], v[210:213], v[24:27]
	v_mfma_f32_16x16x32_bf16 v[12:15], v[148:151], v[218:221], v[12:15]
	v_mfma_f32_16x16x32_bf16 v[8:11], v[164:167], v[218:221], v[8:11]
	v_mfma_f32_16x16x32_bf16 v[60:63], v[160:163], v[192:195], v[60:63]
	v_mfma_f32_16x16x32_bf16 v[56:59], v[168:171], v[192:195], v[56:59]
	v_mfma_f32_16x16x32_bf16 v[44:47], v[160:163], v[200:203], v[44:47]
	v_mfma_f32_16x16x32_bf16 v[40:43], v[168:171], v[200:203], v[40:43]
	v_mfma_f32_16x16x32_bf16 v[28:31], v[160:163], v[214:217], v[28:31]
	v_mfma_f32_16x16x32_bf16 v[24:27], v[168:171], v[214:217], v[24:27]
	v_mfma_f32_16x16x32_bf16 v[12:15], v[160:163], v[222:225], v[12:15]
	v_mfma_f32_16x16x32_bf16 v[8:11], v[168:171], v[222:225], v[8:11]
	s_setprio 0
	s_setprio 3
	v_mfma_f32_16x16x32_bf16 v[52:55], v[172:175], v[188:191], v[52:55]
	v_mfma_f32_16x16x32_bf16 v[48:51], v[180:183], v[188:191], v[48:51]
	v_mfma_f32_16x16x32_bf16 v[36:39], v[172:175], v[196:199], v[36:39]
	v_mfma_f32_16x16x32_bf16 v[32:35], v[180:183], v[196:199], v[32:35]
	v_mfma_f32_16x16x32_bf16 v[20:23], v[172:175], v[210:213], v[20:23]
	v_mfma_f32_16x16x32_bf16 v[16:19], v[180:183], v[210:213], v[16:19]
	v_mfma_f32_16x16x32_bf16 v[4:7], v[172:175], v[218:221], v[4:7]
	v_mfma_f32_16x16x32_bf16 v[0:3], v[180:183], v[218:221], v[0:3]
	v_mfma_f32_16x16x32_bf16 v[52:55], v[176:179], v[192:195], v[52:55]
	v_mfma_f32_16x16x32_bf16 v[48:51], v[184:187], v[192:195], v[48:51]
	v_mfma_f32_16x16x32_bf16 v[36:39], v[176:179], v[200:203], v[36:39]
	v_mfma_f32_16x16x32_bf16 v[32:35], v[184:187], v[200:203], v[32:35]
	v_mfma_f32_16x16x32_bf16 v[20:23], v[176:179], v[214:217], v[20:23]
	v_mfma_f32_16x16x32_bf16 v[16:19], v[184:187], v[214:217], v[16:19]
	v_mfma_f32_16x16x32_bf16 v[4:7], v[176:179], v[222:225], v[4:7]
	v_mfma_f32_16x16x32_bf16 v[0:3], v[184:187], v[222:225], v[0:3]
	s_barrier
	s_setprio 0
	s_add_i32 s65, 0, 0x18000
	v_add_u32_e32 v128, s65, v153
	s_add_i32 s66, 0, 0x1c000
	ds_read_b128 v[148:151], v128
	ds_read_b128 v[160:163], v128 offset:1024
	ds_read_b128 v[164:167], v128 offset:2048
	ds_read_b128 v[168:171], v128 offset:3072
	v_add_u32_e32 v128, s66, v153
	ds_read_b128 v[172:175], v128
	ds_read_b128 v[176:179], v128 offset:1024
	ds_read_b128 v[180:183], v128 offset:2048
	ds_read_b128 v[184:187], v128 offset:3072
	s_add_u32 s0, s40, 0x100000
	s_addc_u32 s1, s41, 0
	s_mov_b32 m0, s44
	ds_read_b128 v[188:191], v158 offset:32768
	ds_read_b128 v[192:195], v158 offset:33792
	ds_read_b128 v[196:199], v158 offset:34816
	ds_read_b128 v[200:203], v158 offset:35840
	ds_read_b128 v[210:213], v158 offset:36864
	ds_read_b128 v[214:217], v158 offset:37888
	ds_read_b128 v[218:221], v158 offset:38912
	global_load_lds_dwordx4 v130, s[0:1]
	s_mov_b32 m0, s45
	ds_read_b128 v[222:225], v158 offset:39936
	global_load_lds_dwordx4 v134, s[0:1]
	s_waitcnt vmcnt(8)
	s_waitcnt lgkmcnt(0)
	s_setprio 3
	s_barrier
	v_mfma_f32_16x16x32_bf16 v[124:127], v[148:151], v[188:191], v[124:127]
	v_mfma_f32_16x16x32_bf16 v[120:123], v[164:167], v[188:191], v[120:123]
	v_mfma_f32_16x16x32_bf16 v[108:111], v[148:151], v[196:199], v[108:111]
	v_mfma_f32_16x16x32_bf16 v[104:107], v[164:167], v[196:199], v[104:107]
	v_mfma_f32_16x16x32_bf16 v[92:95], v[148:151], v[210:213], v[92:95]
	v_mfma_f32_16x16x32_bf16 v[88:91], v[164:167], v[210:213], v[88:91]
	v_mfma_f32_16x16x32_bf16 v[76:79], v[148:151], v[218:221], v[76:79]
	v_mfma_f32_16x16x32_bf16 v[72:75], v[164:167], v[218:221], v[72:75]
	v_mfma_f32_16x16x32_bf16 v[124:127], v[160:163], v[192:195], v[124:127]
	v_mfma_f32_16x16x32_bf16 v[120:123], v[168:171], v[192:195], v[120:123]
	v_mfma_f32_16x16x32_bf16 v[108:111], v[160:163], v[200:203], v[108:111]
	v_mfma_f32_16x16x32_bf16 v[104:107], v[168:171], v[200:203], v[104:107]
	v_mfma_f32_16x16x32_bf16 v[92:95], v[160:163], v[214:217], v[92:95]
	v_mfma_f32_16x16x32_bf16 v[88:91], v[168:171], v[214:217], v[88:91]
	v_mfma_f32_16x16x32_bf16 v[76:79], v[160:163], v[222:225], v[76:79]
	v_mfma_f32_16x16x32_bf16 v[72:75], v[168:171], v[222:225], v[72:75]
	s_setprio 0
	s_setprio 3
	v_mfma_f32_16x16x32_bf16 v[116:119], v[172:175], v[188:191], v[116:119]
	v_mfma_f32_16x16x32_bf16 v[112:115], v[180:183], v[188:191], v[112:115]
	v_mfma_f32_16x16x32_bf16 v[100:103], v[172:175], v[196:199], v[100:103]
	v_mfma_f32_16x16x32_bf16 v[96:99], v[180:183], v[196:199], v[96:99]
	v_mfma_f32_16x16x32_bf16 v[84:87], v[172:175], v[210:213], v[84:87]
	v_mfma_f32_16x16x32_bf16 v[80:83], v[180:183], v[210:213], v[80:83]
	v_mfma_f32_16x16x32_bf16 v[68:71], v[172:175], v[218:221], v[68:71]
	v_mfma_f32_16x16x32_bf16 v[64:67], v[180:183], v[218:221], v[64:67]
	v_mfma_f32_16x16x32_bf16 v[116:119], v[176:179], v[192:195], v[116:119]
	v_mfma_f32_16x16x32_bf16 v[112:115], v[184:187], v[192:195], v[112:115]
	v_mfma_f32_16x16x32_bf16 v[100:103], v[176:179], v[200:203], v[100:103]
	v_mfma_f32_16x16x32_bf16 v[96:99], v[184:187], v[200:203], v[96:99]
	v_mfma_f32_16x16x32_bf16 v[84:87], v[176:179], v[214:217], v[84:87]
	v_mfma_f32_16x16x32_bf16 v[80:83], v[184:187], v[214:217], v[80:83]
	v_mfma_f32_16x16x32_bf16 v[68:71], v[176:179], v[222:225], v[68:71]
	v_mfma_f32_16x16x32_bf16 v[64:67], v[184:187], v[222:225], v[64:67]
	s_barrier
	s_setprio 0
	s_add_i32 s0, s65, s43
	v_lshl_add_u64 v[226:227], v[226:227], 0, s[12:13]
	s_mov_b32 m0, s0
	ds_read_b128 v[188:191], v158 offset:49152
	ds_read_b128 v[192:195], v158 offset:50176
	ds_read_b128 v[196:199], v158 offset:51200
	ds_read_b128 v[200:203], v158 offset:52224
	global_load_lds_dwordx4 v[226:227], off
	s_add_i32 m0, s0, 0x2000
	s_add_u32 s0, s38, 0x100080
	v_lshl_add_u64 v[226:227], v[228:229], 0, s[12:13]
	s_addc_u32 s1, s39, 0
	s_add_i32 s38, s66, s43
	global_load_lds_dwordx4 v[226:227], off
	s_mov_b32 m0, s38
	ds_read_b128 v[222:225], v158 offset:56320
	global_load_lds_dwordx4 v132, s[0:1]
	s_add_i32 m0, s38, 0x2000
	ds_read_b128 v[218:221], v158 offset:55296
	global_load_lds_dwordx4 v136, s[0:1]
	v_lshl_add_u64 v[226:227], v[230:231], 0, s[12:13]
	s_mov_b32 m0, s49
	ds_read_b128 v[214:217], v158 offset:54272
	global_load_lds_dwordx4 v[226:227], off
	v_lshl_add_u64 v[226:227], v[232:233], 0, s[12:13]
	s_mov_b32 m0, s50
	ds_read_b128 v[210:213], v158 offset:53248
	global_load_lds_dwordx4 v[226:227], off
	s_waitcnt vmcnt(8)
	s_waitcnt lgkmcnt(0)
	s_setprio 3
	s_barrier
	v_mfma_f32_16x16x32_bf16 v[60:63], v[148:151], v[188:191], v[60:63]
	v_mfma_f32_16x16x32_bf16 v[56:59], v[164:167], v[188:191], v[56:59]
	v_mfma_f32_16x16x32_bf16 v[44:47], v[148:151], v[196:199], v[44:47]
	v_mfma_f32_16x16x32_bf16 v[40:43], v[164:167], v[196:199], v[40:43]
	v_mfma_f32_16x16x32_bf16 v[28:31], v[148:151], v[210:213], v[28:31]
	v_mfma_f32_16x16x32_bf16 v[24:27], v[164:167], v[210:213], v[24:27]
	v_mfma_f32_16x16x32_bf16 v[12:15], v[148:151], v[218:221], v[12:15]
	v_mfma_f32_16x16x32_bf16 v[8:11], v[164:167], v[218:221], v[8:11]
	v_mfma_f32_16x16x32_bf16 v[60:63], v[160:163], v[192:195], v[60:63]
	v_mfma_f32_16x16x32_bf16 v[56:59], v[168:171], v[192:195], v[56:59]
	v_mfma_f32_16x16x32_bf16 v[44:47], v[160:163], v[200:203], v[44:47]
	v_mfma_f32_16x16x32_bf16 v[40:43], v[168:171], v[200:203], v[40:43]
	v_mfma_f32_16x16x32_bf16 v[28:31], v[160:163], v[214:217], v[28:31]
	v_mfma_f32_16x16x32_bf16 v[24:27], v[168:171], v[214:217], v[24:27]
	v_mfma_f32_16x16x32_bf16 v[12:15], v[160:163], v[222:225], v[12:15]
	v_mfma_f32_16x16x32_bf16 v[8:11], v[168:171], v[222:225], v[8:11]
	s_setprio 0
	s_setprio 3
	v_mfma_f32_16x16x32_bf16 v[52:55], v[172:175], v[188:191], v[52:55]
	v_mfma_f32_16x16x32_bf16 v[48:51], v[180:183], v[188:191], v[48:51]
	v_mfma_f32_16x16x32_bf16 v[36:39], v[172:175], v[196:199], v[36:39]
	v_mfma_f32_16x16x32_bf16 v[32:35], v[180:183], v[196:199], v[32:35]
	v_mfma_f32_16x16x32_bf16 v[20:23], v[172:175], v[210:213], v[20:23]
	v_mfma_f32_16x16x32_bf16 v[16:19], v[180:183], v[210:213], v[16:19]
	v_mfma_f32_16x16x32_bf16 v[4:7], v[172:175], v[218:221], v[4:7]
	v_mfma_f32_16x16x32_bf16 v[0:3], v[180:183], v[218:221], v[0:3]
	v_mfma_f32_16x16x32_bf16 v[52:55], v[176:179], v[192:195], v[52:55]
	v_mfma_f32_16x16x32_bf16 v[48:51], v[184:187], v[192:195], v[48:51]
	v_mfma_f32_16x16x32_bf16 v[36:39], v[176:179], v[200:203], v[36:39]
	v_mfma_f32_16x16x32_bf16 v[32:35], v[184:187], v[200:203], v[32:35]
	v_mfma_f32_16x16x32_bf16 v[20:23], v[176:179], v[214:217], v[20:23]
	v_mfma_f32_16x16x32_bf16 v[16:19], v[184:187], v[214:217], v[16:19]
	v_mfma_f32_16x16x32_bf16 v[4:7], v[176:179], v[222:225], v[4:7]
	v_mfma_f32_16x16x32_bf16 v[0:3], v[184:187], v[222:225], v[0:3]
	s_barrier
	s_setprio 0
	s_add_u32 s36, s36, 0x100
	s_addc_u32 s37, s37, 0
	s_add_i32 s64, s64, 2
	s_add_u32 s62, s62, 0x100
	s_addc_u32 s63, s63, 0
	s_cmp_gt_u32 s64, 61
	s_cbranch_scc0 .LBB0_1813
	s_and_b64 vcc, exec, s[14:15]
	s_cbranch_vccz .LBB0_1816
	s_barrier

.LBB0_1833:
	ds_read_b128 v[24:27], v193
	ds_read_b128 v[28:31], v193 offset:1024
	ds_read_b128 v[16:19], v193 offset:2048
	ds_read_b128 v[20:23], v193 offset:3072
	ds_read_b128 v[8:11], v194
	ds_read_b128 v[12:15], v194 offset:1024
	ds_read_b128 v[0:3], v194 offset:2048
	ds_read_b128 v[4:7], v194 offset:3072
	s_add_u32 s0, s36, 0xfff80080
	s_addc_u32 s1, s37, -1
	s_cmp_eq_u32 s65, 28
	s_cselect_b32 s41, s26, s1
	s_cselect_b32 s40, s27, s0
	s_cselect_b32 s39, s17, s64
	s_cselect_b32 s38, s31, s63
	s_add_i32 m0, s35, 0xc000
	ds_read_b128 v[180:183], v195
	ds_read_b128 v[184:187], v195 offset:1024
	ds_read_b128 v[210:213], v195 offset:2048
	ds_read_b128 v[214:217], v195 offset:3072
	ds_read_b128 v[218:221], v195 offset:4096
	ds_read_b128 v[222:225], v195 offset:5120
	ds_read_b128 v[226:229], v195 offset:6144
	global_load_lds_dwordx4 v172, s[36:37]
	s_add_i32 m0, s35, 0xe000
	ds_read_b128 v[230:233], v195 offset:7168
	global_load_lds_dwordx4 v174, s[36:37]
	s_waitcnt vmcnt(8)
	s_waitcnt lgkmcnt(0)
	s_setprio 3
	s_barrier
	v_mfma_scale_f32_16x16x128_f8f6f4 v[152:155], v[24:31], v[180:187], v[152:155], v188, v188 op_sel_hi:[0,0,0]
	v_mfma_scale_f32_16x16x128_f8f6f4 v[148:151], v[16:23], v[180:187], v[148:151], v188, v188 op_sel_hi:[0,0,0]
	v_mfma_scale_f32_16x16x128_f8f6f4 v[140:143], v[24:31], v[210:217], v[140:143], v188, v188 op_sel_hi:[0,0,0]
	v_mfma_scale_f32_16x16x128_f8f6f4 v[132:135], v[16:23], v[210:217], v[132:135], v188, v188 op_sel_hi:[0,0,0]
	v_mfma_scale_f32_16x16x128_f8f6f4 v[124:127], v[24:31], v[218:225], v[124:127], v188, v188 op_sel_hi:[0,0,0]
	v_mfma_scale_f32_16x16x128_f8f6f4 v[120:123], v[16:23], v[218:225], v[120:123], v188, v188 op_sel_hi:[0,0,0]
	v_mfma_scale_f32_16x16x128_f8f6f4 v[108:111], v[24:31], v[226:233], v[108:111], v188, v188 op_sel_hi:[0,0,0]
	v_mfma_scale_f32_16x16x128_f8f6f4 v[100:103], v[16:23], v[226:233], v[100:103], v188, v188 op_sel_hi:[0,0,0]
	s_setprio 0
	s_setprio 3
	v_mfma_scale_f32_16x16x128_f8f6f4 v[156:159], v[8:15], v[180:187], v[156:159], v188, v188 op_sel_hi:[0,0,0]
	v_mfma_scale_f32_16x16x128_f8f6f4 v[144:147], v[0:7], v[180:187], v[144:147], v188, v188 op_sel_hi:[0,0,0]
	v_mfma_scale_f32_16x16x128_f8f6f4 v[136:139], v[8:15], v[210:217], v[136:139], v188, v188 op_sel_hi:[0,0,0]
	v_mfma_scale_f32_16x16x128_f8f6f4 v[128:131], v[0:7], v[210:217], v[128:131], v188, v188 op_sel_hi:[0,0,0]
	v_mfma_scale_f32_16x16x128_f8f6f4 v[116:119], v[8:15], v[218:225], v[116:119], v188, v188 op_sel_hi:[0,0,0]
	v_mfma_scale_f32_16x16x128_f8f6f4 v[112:115], v[0:7], v[218:225], v[112:115], v188, v188 op_sel_hi:[0,0,0]
	v_mfma_scale_f32_16x16x128_f8f6f4 v[104:107], v[8:15], v[226:233], v[104:107], v188, v188 op_sel_hi:[0,0,0]
	v_mfma_scale_f32_16x16x128_f8f6f4 v[96:99], v[0:7], v[226:233], v[96:99], v188, v188 op_sel_hi:[0,0,0]
	s_barrier
	s_setprio 0
	s_add_i32 s0, s56, s45
	v_lshl_add_u64 v[180:181], s[38:39], 0, v[164:165]
	s_mov_b32 m0, s0
	ds_read_b128 v[210:213], v195 offset:16384
	ds_read_b128 v[214:217], v195 offset:17408
	ds_read_b128 v[218:221], v195 offset:18432
	ds_read_b128 v[222:225], v195 offset:19456
	ds_read_b128 v[226:229], v195 offset:20480
	global_load_lds_dwordx4 v[180:181], off
	s_add_i32 m0, s0, 0x2000
	s_add_u32 s0, s38, 0x80000
	v_lshl_add_u64 v[182:183], s[38:39], 0, v[168:169]
	s_addc_u32 s1, s39, 0
	s_add_i32 s66, s57, s45
	global_load_lds_dwordx4 v[182:183], off
	s_mov_b32 m0, s66
	v_lshl_add_u64 v[186:187], s[40:41], 0, v[166:167]
	global_load_lds_dwordx4 v164, s[0:1]
	s_add_i32 m0, s66, 0x2000
	ds_read_b128 v[238:241], v195 offset:23552
	global_load_lds_dwordx4 v168, s[0:1]
	v_lshl_add_u64 v[184:185], s[40:41], 0, v[162:163]
	s_mov_b32 m0, s35
	ds_read_b128 v[234:237], v195 offset:22528
	global_load_lds_dwordx4 v[184:185], off
	s_mov_b32 m0, s46
	ds_read_b128 v[230:233], v195 offset:21504
	global_load_lds_dwordx4 v[186:187], off
	s_waitcnt vmcnt(8)
	s_waitcnt lgkmcnt(0)
	s_setprio 3
	s_barrier
	v_mfma_scale_f32_16x16x128_f8f6f4 v[92:95], v[24:31], v[210:217], v[92:95], v188, v188 op_sel_hi:[0,0,0]
	v_mfma_scale_f32_16x16x128_f8f6f4 v[88:91], v[16:23], v[210:217], v[88:91], v188, v188 op_sel_hi:[0,0,0]
	v_mfma_scale_f32_16x16x128_f8f6f4 v[76:79], v[24:31], v[218:225], v[76:79], v188, v188 op_sel_hi:[0,0,0]
	v_mfma_scale_f32_16x16x128_f8f6f4 v[68:71], v[16:23], v[218:225], v[68:71], v188, v188 op_sel_hi:[0,0,0]
	v_mfma_scale_f32_16x16x128_f8f6f4 v[60:63], v[24:31], v[226:233], v[60:63], v188, v188 op_sel_hi:[0,0,0]
	v_mfma_scale_f32_16x16x128_f8f6f4 v[56:59], v[16:23], v[226:233], v[56:59], v188, v188 op_sel_hi:[0,0,0]
	v_mfma_scale_f32_16x16x128_f8f6f4 v[44:47], v[24:31], v[234:241], v[44:47], v188, v188 op_sel_hi:[0,0,0]
	v_mfma_scale_f32_16x16x128_f8f6f4 v[40:43], v[16:23], v[234:241], v[40:43], v188, v188 op_sel_hi:[0,0,0]
	s_setprio 0
	s_setprio 3
	v_mfma_scale_f32_16x16x128_f8f6f4 v[84:87], v[8:15], v[210:217], v[84:87], v188, v188 op_sel_hi:[0,0,0]
	v_mfma_scale_f32_16x16x128_f8f6f4 v[80:83], v[0:7], v[210:217], v[80:83], v188, v188 op_sel_hi:[0,0,0]
	v_mfma_scale_f32_16x16x128_f8f6f4 v[72:75], v[8:15], v[218:225], v[72:75], v188, v188 op_sel_hi:[0,0,0]
	v_mfma_scale_f32_16x16x128_f8f6f4 v[64:67], v[0:7], v[218:225], v[64:67], v188, v188 op_sel_hi:[0,0,0]
	v_mfma_scale_f32_16x16x128_f8f6f4 v[52:55], v[8:15], v[226:233], v[52:55], v188, v188 op_sel_hi:[0,0,0]
	v_mfma_scale_f32_16x16x128_f8f6f4 v[48:51], v[0:7], v[226:233], v[48:51], v188, v188 op_sel_hi:[0,0,0]
	v_mfma_scale_f32_16x16x128_f8f6f4 v[36:39], v[8:15], v[234:241], v[36:39], v188, v188 op_sel_hi:[0,0,0]
	v_mfma_scale_f32_16x16x128_f8f6f4 v[32:35], v[0:7], v[234:241], v[32:35], v188, v188 op_sel_hi:[0,0,0]
	s_barrier
	s_setprio 0
	s_add_i32 s66, 0, 0x18000
	s_add_i32 s67, 0, 0x1c000
	v_add_u32_e32 v12, s66, v190
	v_add_u32_e32 v28, s67, v190
	ds_read_b128 v[0:3], v12
	ds_read_b128 v[4:7], v12 offset:1024
	ds_read_b128 v[8:11], v12 offset:2048
	ds_read_b128 v[12:15], v12 offset:3072
	ds_read_b128 v[16:19], v28
	ds_read_b128 v[20:23], v28 offset:1024
	ds_read_b128 v[24:27], v28 offset:2048
	ds_read_b128 v[28:31], v28 offset:3072
	s_add_u32 s0, s40, 0x80000
	s_addc_u32 s1, s41, 0
	s_mov_b32 m0, s47
	ds_read_b128 v[210:213], v195 offset:32768
	ds_read_b128 v[214:217], v195 offset:33792
	ds_read_b128 v[218:221], v195 offset:34816
	ds_read_b128 v[222:225], v195 offset:35840
	ds_read_b128 v[226:229], v195 offset:36864
	ds_read_b128 v[230:233], v195 offset:37888
	ds_read_b128 v[234:237], v195 offset:38912
	global_load_lds_dwordx4 v162, s[0:1]
	s_mov_b32 m0, s48
	ds_read_b128 v[238:241], v195 offset:39936
	global_load_lds_dwordx4 v166, s[0:1]
	s_waitcnt vmcnt(8)
	s_waitcnt lgkmcnt(0)
	s_setprio 3
	s_barrier
	v_mfma_scale_f32_16x16x128_f8f6f4 v[152:155], v[0:7], v[210:217], v[152:155], v188, v188 op_sel_hi:[0,0,0]
	v_mfma_scale_f32_16x16x128_f8f6f4 v[148:151], v[8:15], v[210:217], v[148:151], v188, v188 op_sel_hi:[0,0,0]
	v_mfma_scale_f32_16x16x128_f8f6f4 v[140:143], v[0:7], v[218:225], v[140:143], v188, v188 op_sel_hi:[0,0,0]
	v_mfma_scale_f32_16x16x128_f8f6f4 v[132:135], v[8:15], v[218:225], v[132:135], v188, v188 op_sel_hi:[0,0,0]
	v_mfma_scale_f32_16x16x128_f8f6f4 v[124:127], v[0:7], v[226:233], v[124:127], v188, v188 op_sel_hi:[0,0,0]
	v_mfma_scale_f32_16x16x128_f8f6f4 v[120:123], v[8:15], v[226:233], v[120:123], v188, v188 op_sel_hi:[0,0,0]
	v_mfma_scale_f32_16x16x128_f8f6f4 v[108:111], v[0:7], v[234:241], v[108:111], v188, v188 op_sel_hi:[0,0,0]
	v_mfma_scale_f32_16x16x128_f8f6f4 v[100:103], v[8:15], v[234:241], v[100:103], v188, v188 op_sel_hi:[0,0,0]
	s_setprio 0
	s_setprio 3
	v_mfma_scale_f32_16x16x128_f8f6f4 v[156:159], v[16:23], v[210:217], v[156:159], v188, v188 op_sel_hi:[0,0,0]
	v_mfma_scale_f32_16x16x128_f8f6f4 v[144:147], v[24:31], v[210:217], v[144:147], v188, v188 op_sel_hi:[0,0,0]
	v_mfma_scale_f32_16x16x128_f8f6f4 v[136:139], v[16:23], v[218:225], v[136:139], v188, v188 op_sel_hi:[0,0,0]
	v_mfma_scale_f32_16x16x128_f8f6f4 v[128:131], v[24:31], v[218:225], v[128:131], v188, v188 op_sel_hi:[0,0,0]
	v_mfma_scale_f32_16x16x128_f8f6f4 v[116:119], v[16:23], v[226:233], v[116:119], v188, v188 op_sel_hi:[0,0,0]
	v_mfma_scale_f32_16x16x128_f8f6f4 v[112:115], v[24:31], v[226:233], v[112:115], v188, v188 op_sel_hi:[0,0,0]
	v_mfma_scale_f32_16x16x128_f8f6f4 v[104:107], v[16:23], v[234:241], v[104:107], v188, v188 op_sel_hi:[0,0,0]
	v_mfma_scale_f32_16x16x128_f8f6f4 v[96:99], v[24:31], v[234:241], v[96:99], v188, v188 op_sel_hi:[0,0,0]
	s_barrier
	s_setprio 0
	s_add_i32 s0, s66, s45
	v_lshl_add_u64 v[180:181], v[180:181], 0, s[12:13]
	s_mov_b32 m0, s0
	ds_read_b128 v[210:213], v195 offset:49152
	ds_read_b128 v[214:217], v195 offset:50176
	ds_read_b128 v[218:221], v195 offset:51200
	ds_read_b128 v[222:225], v195 offset:52224
	global_load_lds_dwordx4 v[180:181], off
	s_add_i32 m0, s0, 0x2000
	s_add_u32 s0, s38, 0x80080
	v_lshl_add_u64 v[180:181], v[182:183], 0, s[12:13]
	s_addc_u32 s1, s39, 0
	s_add_i32 s38, s67, s45
	global_load_lds_dwordx4 v[180:181], off
	s_mov_b32 m0, s38
	ds_read_b128 v[238:241], v195 offset:56320
	global_load_lds_dwordx4 v164, s[0:1]
	s_add_i32 m0, s38, 0x2000
	ds_read_b128 v[234:237], v195 offset:55296
	global_load_lds_dwordx4 v168, s[0:1]
	v_lshl_add_u64 v[180:181], v[184:185], 0, s[12:13]
	s_mov_b32 m0, s51
	ds_read_b128 v[230:233], v195 offset:54272
	global_load_lds_dwordx4 v[180:181], off
	v_lshl_add_u64 v[180:181], v[186:187], 0, s[12:13]
	s_mov_b32 m0, s52
	ds_read_b128 v[226:229], v195 offset:53248
	global_load_lds_dwordx4 v[180:181], off
	s_waitcnt vmcnt(8)
	s_waitcnt lgkmcnt(0)
	s_setprio 3
	s_barrier
	v_mfma_scale_f32_16x16x128_f8f6f4 v[92:95], v[0:7], v[210:217], v[92:95], v188, v188 op_sel_hi:[0,0,0]
	v_mfma_scale_f32_16x16x128_f8f6f4 v[88:91], v[8:15], v[210:217], v[88:91], v188, v188 op_sel_hi:[0,0,0]
	v_mfma_scale_f32_16x16x128_f8f6f4 v[76:79], v[0:7], v[218:225], v[76:79], v188, v188 op_sel_hi:[0,0,0]
	v_mfma_scale_f32_16x16x128_f8f6f4 v[68:71], v[8:15], v[218:225], v[68:71], v188, v188 op_sel_hi:[0,0,0]
	v_mfma_scale_f32_16x16x128_f8f6f4 v[60:63], v[0:7], v[226:233], v[60:63], v188, v188 op_sel_hi:[0,0,0]
	v_mfma_scale_f32_16x16x128_f8f6f4 v[56:59], v[8:15], v[226:233], v[56:59], v188, v188 op_sel_hi:[0,0,0]
	v_mfma_scale_f32_16x16x128_f8f6f4 v[44:47], v[0:7], v[234:241], v[44:47], v188, v188 op_sel_hi:[0,0,0]
	v_mfma_scale_f32_16x16x128_f8f6f4 v[40:43], v[8:15], v[234:241], v[40:43], v188, v188 op_sel_hi:[0,0,0]
	s_setprio 0
	s_setprio 3
	v_mfma_scale_f32_16x16x128_f8f6f4 v[84:87], v[16:23], v[210:217], v[84:87], v188, v188 op_sel_hi:[0,0,0]
	v_mfma_scale_f32_16x16x128_f8f6f4 v[80:83], v[24:31], v[210:217], v[80:83], v188, v188 op_sel_hi:[0,0,0]
	v_mfma_scale_f32_16x16x128_f8f6f4 v[72:75], v[16:23], v[218:225], v[72:75], v188, v188 op_sel_hi:[0,0,0]
	v_mfma_scale_f32_16x16x128_f8f6f4 v[64:67], v[24:31], v[218:225], v[64:67], v188, v188 op_sel_hi:[0,0,0]
	v_mfma_scale_f32_16x16x128_f8f6f4 v[52:55], v[16:23], v[226:233], v[52:55], v188, v188 op_sel_hi:[0,0,0]
	v_mfma_scale_f32_16x16x128_f8f6f4 v[48:51], v[24:31], v[226:233], v[48:51], v188, v188 op_sel_hi:[0,0,0]
	v_mfma_scale_f32_16x16x128_f8f6f4 v[36:39], v[16:23], v[234:241], v[36:39], v188, v188 op_sel_hi:[0,0,0]
	v_mfma_scale_f32_16x16x128_f8f6f4 v[32:35], v[24:31], v[234:241], v[32:35], v188, v188 op_sel_hi:[0,0,0]
	s_barrier
	s_setprio 0
	s_add_u32 s36, s36, 0x100
	s_addc_u32 s37, s37, 0
	s_add_i32 s65, s65, 2
	s_add_u32 s63, s63, 0x100
	s_addc_u32 s64, s64, 0
	s_cmp_gt_u32 s65, 29
	s_cbranch_scc0 .LBB0_1833
	s_and_b64 vcc, exec, s[14:15]
	s_cbranch_vccz .LBB0_1836
	s_barrier

.LBB0_1974:
	v_add_u32_e32 v0, s65, v182
	v_add_u32_e32 v4, s66, v182
	ds_read_b128 v[24:27], v0
	ds_read_b128 v[28:31], v0 offset:1024
	ds_read_b128 v[16:19], v0 offset:2048
	ds_read_b128 v[20:23], v0 offset:3072
	ds_read_b128 v[8:11], v4
	ds_read_b128 v[12:15], v4 offset:1024
	ds_read_b128 v[0:3], v4 offset:2048
	ds_read_b128 v[4:7], v4 offset:3072
	s_add_i32 s35, s35, 2
	s_lshr_b32 s0, s35, 5
	s_mul_hi_u32 s1, s0, 0x4100000
	s_mul_i32 s0, s0, 0x4100000
	s_add_u32 s0, s46, s0
	s_addc_u32 s1, s47, s1
	s_and_b32 s37, s37, 0xf00
	s_add_u32 s0, s0, s37
	s_addc_u32 s1, s1, 0
	s_add_u32 s0, s0, 0x80080
	s_addc_u32 s1, s1, 0
	s_add_i32 m0, s43, 0xc000
	ds_read_b128 v[172:175], v184
	ds_read_b128 v[176:179], v184 offset:1024
	ds_read_b128 v[186:189], v184 offset:2048
	ds_read_b128 v[190:193], v184 offset:3072
	ds_read_b128 v[194:197], v184 offset:4096
	ds_read_b128 v[198:201], v184 offset:5120
	ds_read_b128 v[210:213], v184 offset:6144
	global_load_lds_dwordx4 v160, s[0:1]
	s_add_i32 m0, s43, 0xe000
	ds_read_b128 v[214:217], v184 offset:7168
	global_load_lds_dwordx4 v164, s[0:1]
	s_waitcnt vmcnt(8)
	s_waitcnt lgkmcnt(0)
	s_setprio 3
	s_barrier
	v_mfma_scale_f32_16x16x128_f8f6f4 v[156:159], v[24:31], v[172:179], v[156:159], v180, v180 op_sel_hi:[0,0,0]
	v_mfma_scale_f32_16x16x128_f8f6f4 v[152:155], v[16:23], v[172:179], v[152:155], v180, v180 op_sel_hi:[0,0,0]
	v_mfma_scale_f32_16x16x128_f8f6f4 v[144:147], v[24:31], v[186:193], v[144:147], v180, v180 op_sel_hi:[0,0,0]
	v_mfma_scale_f32_16x16x128_f8f6f4 v[136:139], v[16:23], v[186:193], v[136:139], v180, v180 op_sel_hi:[0,0,0]
	v_mfma_scale_f32_16x16x128_f8f6f4 v[128:131], v[24:31], v[194:201], v[128:131], v180, v180 op_sel_hi:[0,0,0]
	v_mfma_scale_f32_16x16x128_f8f6f4 v[120:123], v[16:23], v[194:201], v[120:123], v180, v180 op_sel_hi:[0,0,0]
	v_mfma_scale_f32_16x16x128_f8f6f4 v[112:115], v[24:31], v[210:217], v[112:115], v180, v180 op_sel_hi:[0,0,0]
	v_mfma_scale_f32_16x16x128_f8f6f4 v[104:107], v[16:23], v[210:217], v[104:107], v180, v180 op_sel_hi:[0,0,0]
	s_setprio 0
	s_setprio 3
	v_mfma_scale_f32_16x16x128_f8f6f4 v[148:151], v[8:15], v[172:179], v[148:151], v180, v180 op_sel_hi:[0,0,0]
	v_mfma_scale_f32_16x16x128_f8f6f4 v[140:143], v[0:7], v[172:179], v[140:143], v180, v180 op_sel_hi:[0,0,0]
	v_mfma_scale_f32_16x16x128_f8f6f4 v[132:135], v[8:15], v[186:193], v[132:135], v180, v180 op_sel_hi:[0,0,0]
	v_mfma_scale_f32_16x16x128_f8f6f4 v[124:127], v[0:7], v[186:193], v[124:127], v180, v180 op_sel_hi:[0,0,0]
	v_mfma_scale_f32_16x16x128_f8f6f4 v[116:119], v[8:15], v[194:201], v[116:119], v180, v180 op_sel_hi:[0,0,0]
	v_mfma_scale_f32_16x16x128_f8f6f4 v[108:111], v[0:7], v[194:201], v[108:111], v180, v180 op_sel_hi:[0,0,0]
	v_mfma_scale_f32_16x16x128_f8f6f4 v[100:103], v[8:15], v[210:217], v[100:103], v180, v180 op_sel_hi:[0,0,0]
	v_mfma_scale_f32_16x16x128_f8f6f4 v[96:99], v[0:7], v[210:217], v[96:99], v180, v180 op_sel_hi:[0,0,0]
	s_barrier
	s_setprio 0
	s_add_i32 s0, s65, s58
	v_lshl_add_u64 v[172:173], s[52:53], 0, v[162:163]
	s_mov_b32 m0, s0
	ds_read_b128 v[186:189], v184 offset:16384
	ds_read_b128 v[190:193], v184 offset:17408
	ds_read_b128 v[194:197], v184 offset:18432
	ds_read_b128 v[198:201], v184 offset:19456
	ds_read_b128 v[210:213], v184 offset:20480
	global_load_lds_dwordx4 v[172:173], off
	s_add_i32 m0, s0, 0x2000
	s_add_u32 s0, s52, 0x80000
	v_lshl_add_u64 v[174:175], s[52:53], 0, v[166:167]
	s_addc_u32 s1, s53, 0
	s_add_i32 s37, s66, s58
	global_load_lds_dwordx4 v[174:175], off
	s_mov_b32 m0, s37
	v_lshl_add_u64 v[178:179], s[54:55], 0, v[164:165]
	global_load_lds_dwordx4 v162, s[0:1]
	s_add_i32 m0, s37, 0x2000
	ds_read_b128 v[222:225], v184 offset:23552
	global_load_lds_dwordx4 v166, s[0:1]
	v_lshl_add_u64 v[176:177], s[54:55], 0, v[160:161]
	s_mov_b32 m0, s43
	ds_read_b128 v[218:221], v184 offset:22528
	global_load_lds_dwordx4 v[176:177], off
	s_mov_b32 m0, s59
	ds_read_b128 v[214:217], v184 offset:21504
	global_load_lds_dwordx4 v[178:179], off
	s_waitcnt vmcnt(8)
	s_waitcnt lgkmcnt(0)
	s_setprio 3
	s_barrier
	v_mfma_scale_f32_16x16x128_f8f6f4 v[92:95], v[24:31], v[186:193], v[92:95], v180, v180 op_sel_hi:[0,0,0]
	v_mfma_scale_f32_16x16x128_f8f6f4 v[88:91], v[16:23], v[186:193], v[88:91], v180, v180 op_sel_hi:[0,0,0]
	v_mfma_scale_f32_16x16x128_f8f6f4 v[80:83], v[24:31], v[194:201], v[80:83], v180, v180 op_sel_hi:[0,0,0]
	v_mfma_scale_f32_16x16x128_f8f6f4 v[72:75], v[16:23], v[194:201], v[72:75], v180, v180 op_sel_hi:[0,0,0]
	v_mfma_scale_f32_16x16x128_f8f6f4 v[64:67], v[24:31], v[210:217], v[64:67], v180, v180 op_sel_hi:[0,0,0]
	v_mfma_scale_f32_16x16x128_f8f6f4 v[56:59], v[16:23], v[210:217], v[56:59], v180, v180 op_sel_hi:[0,0,0]
	v_mfma_scale_f32_16x16x128_f8f6f4 v[48:51], v[24:31], v[218:225], v[48:51], v180, v180 op_sel_hi:[0,0,0]
	v_mfma_scale_f32_16x16x128_f8f6f4 v[40:43], v[16:23], v[218:225], v[40:43], v180, v180 op_sel_hi:[0,0,0]
	s_setprio 0
	s_setprio 3
	v_mfma_scale_f32_16x16x128_f8f6f4 v[84:87], v[8:15], v[186:193], v[84:87], v180, v180 op_sel_hi:[0,0,0]
	v_mfma_scale_f32_16x16x128_f8f6f4 v[76:79], v[0:7], v[186:193], v[76:79], v180, v180 op_sel_hi:[0,0,0]
	v_mfma_scale_f32_16x16x128_f8f6f4 v[68:71], v[8:15], v[194:201], v[68:71], v180, v180 op_sel_hi:[0,0,0]
	v_mfma_scale_f32_16x16x128_f8f6f4 v[60:63], v[0:7], v[194:201], v[60:63], v180, v180 op_sel_hi:[0,0,0]
	v_mfma_scale_f32_16x16x128_f8f6f4 v[52:55], v[8:15], v[210:217], v[52:55], v180, v180 op_sel_hi:[0,0,0]
	v_mfma_scale_f32_16x16x128_f8f6f4 v[44:47], v[0:7], v[210:217], v[44:47], v180, v180 op_sel_hi:[0,0,0]
	v_mfma_scale_f32_16x16x128_f8f6f4 v[36:39], v[8:15], v[218:225], v[36:39], v180, v180 op_sel_hi:[0,0,0]
	v_mfma_scale_f32_16x16x128_f8f6f4 v[32:35], v[0:7], v[218:225], v[32:35], v180, v180 op_sel_hi:[0,0,0]
	s_barrier
	s_setprio 0
	s_add_i32 s37, 0, 0x18000
	s_add_i32 s56, 0, 0x1c000
	v_add_u32_e32 v12, s37, v182
	v_add_u32_e32 v28, s56, v182
	ds_read_b128 v[0:3], v12
	ds_read_b128 v[4:7], v12 offset:1024
	ds_read_b128 v[8:11], v12 offset:2048
	ds_read_b128 v[12:15], v12 offset:3072
	ds_read_b128 v[16:19], v28
	ds_read_b128 v[20:23], v28 offset:1024
	ds_read_b128 v[24:27], v28 offset:2048
	ds_read_b128 v[28:31], v28 offset:3072
	s_add_u32 s0, s54, 0x80000
	s_addc_u32 s1, s55, 0
	s_mov_b32 m0, s60
	ds_read_b128 v[186:189], v184 offset:32768
	ds_read_b128 v[190:193], v184 offset:33792
	ds_read_b128 v[194:197], v184 offset:34816
	ds_read_b128 v[198:201], v184 offset:35840
	ds_read_b128 v[210:213], v184 offset:36864
	ds_read_b128 v[214:217], v184 offset:37888
	ds_read_b128 v[218:221], v184 offset:38912
	global_load_lds_dwordx4 v160, s[0:1]
	s_mov_b32 m0, s61
	ds_read_b128 v[222:225], v184 offset:39936
	global_load_lds_dwordx4 v164, s[0:1]
	s_waitcnt vmcnt(8)
	s_waitcnt lgkmcnt(0)
	s_setprio 3
	s_barrier
	v_mfma_scale_f32_16x16x128_f8f6f4 v[156:159], v[0:7], v[186:193], v[156:159], v180, v180 op_sel_hi:[0,0,0]
	v_mfma_scale_f32_16x16x128_f8f6f4 v[152:155], v[8:15], v[186:193], v[152:155], v180, v180 op_sel_hi:[0,0,0]
	v_mfma_scale_f32_16x16x128_f8f6f4 v[144:147], v[0:7], v[194:201], v[144:147], v180, v180 op_sel_hi:[0,0,0]
	v_mfma_scale_f32_16x16x128_f8f6f4 v[136:139], v[8:15], v[194:201], v[136:139], v180, v180 op_sel_hi:[0,0,0]
	v_mfma_scale_f32_16x16x128_f8f6f4 v[128:131], v[0:7], v[210:217], v[128:131], v180, v180 op_sel_hi:[0,0,0]
	v_mfma_scale_f32_16x16x128_f8f6f4 v[120:123], v[8:15], v[210:217], v[120:123], v180, v180 op_sel_hi:[0,0,0]
	v_mfma_scale_f32_16x16x128_f8f6f4 v[112:115], v[0:7], v[218:225], v[112:115], v180, v180 op_sel_hi:[0,0,0]
	v_mfma_scale_f32_16x16x128_f8f6f4 v[104:107], v[8:15], v[218:225], v[104:107], v180, v180 op_sel_hi:[0,0,0]
	s_setprio 0
	s_setprio 3
	v_mfma_scale_f32_16x16x128_f8f6f4 v[148:151], v[16:23], v[186:193], v[148:151], v180, v180 op_sel_hi:[0,0,0]
	v_mfma_scale_f32_16x16x128_f8f6f4 v[140:143], v[24:31], v[186:193], v[140:143], v180, v180 op_sel_hi:[0,0,0]
	v_mfma_scale_f32_16x16x128_f8f6f4 v[132:135], v[16:23], v[194:201], v[132:135], v180, v180 op_sel_hi:[0,0,0]
	v_mfma_scale_f32_16x16x128_f8f6f4 v[124:127], v[24:31], v[194:201], v[124:127], v180, v180 op_sel_hi:[0,0,0]
	v_mfma_scale_f32_16x16x128_f8f6f4 v[116:119], v[16:23], v[210:217], v[116:119], v180, v180 op_sel_hi:[0,0,0]
	v_mfma_scale_f32_16x16x128_f8f6f4 v[108:111], v[24:31], v[210:217], v[108:111], v180, v180 op_sel_hi:[0,0,0]
	v_mfma_scale_f32_16x16x128_f8f6f4 v[100:103], v[16:23], v[218:225], v[100:103], v180, v180 op_sel_hi:[0,0,0]
	v_mfma_scale_f32_16x16x128_f8f6f4 v[96:99], v[24:31], v[218:225], v[96:99], v180, v180 op_sel_hi:[0,0,0]
	s_barrier
	s_setprio 0
	s_add_i32 s0, s37, s58
	v_lshl_add_u64 v[172:173], v[172:173], 0, s[12:13]
	s_mov_b32 m0, s0
	ds_read_b128 v[186:189], v184 offset:49152
	ds_read_b128 v[190:193], v184 offset:50176
	ds_read_b128 v[194:197], v184 offset:51200
	ds_read_b128 v[198:201], v184 offset:52224
	global_load_lds_dwordx4 v[172:173], off
	s_add_i32 m0, s0, 0x2000
	s_add_u32 s0, s52, 0x80080
	v_lshl_add_u64 v[172:173], v[174:175], 0, s[12:13]
	s_addc_u32 s1, s53, 0
	s_add_i32 s37, s56, s58
	global_load_lds_dwordx4 v[172:173], off
	s_mov_b32 m0, s37
	ds_read_b128 v[222:225], v184 offset:56320
	global_load_lds_dwordx4 v162, s[0:1]
	s_add_i32 m0, s37, 0x2000
	ds_read_b128 v[218:221], v184 offset:55296
	global_load_lds_dwordx4 v166, s[0:1]
	v_lshl_add_u64 v[172:173], v[176:177], 0, s[12:13]
	s_mov_b32 m0, s62
	ds_read_b128 v[214:217], v184 offset:54272
	global_load_lds_dwordx4 v[172:173], off
	v_lshl_add_u64 v[172:173], v[178:179], 0, s[12:13]
	s_mov_b32 m0, s63
	ds_read_b128 v[210:213], v184 offset:53248
	global_load_lds_dwordx4 v[172:173], off
	s_waitcnt vmcnt(8)
	s_waitcnt lgkmcnt(0)
	s_setprio 3
	s_barrier
	v_mfma_scale_f32_16x16x128_f8f6f4 v[92:95], v[0:7], v[186:193], v[92:95], v180, v180 op_sel_hi:[0,0,0]
	v_mfma_scale_f32_16x16x128_f8f6f4 v[88:91], v[8:15], v[186:193], v[88:91], v180, v180 op_sel_hi:[0,0,0]
	v_mfma_scale_f32_16x16x128_f8f6f4 v[80:83], v[0:7], v[194:201], v[80:83], v180, v180 op_sel_hi:[0,0,0]
	v_mfma_scale_f32_16x16x128_f8f6f4 v[72:75], v[8:15], v[194:201], v[72:75], v180, v180 op_sel_hi:[0,0,0]
	v_mfma_scale_f32_16x16x128_f8f6f4 v[64:67], v[0:7], v[210:217], v[64:67], v180, v180 op_sel_hi:[0,0,0]
	v_mfma_scale_f32_16x16x128_f8f6f4 v[56:59], v[8:15], v[210:217], v[56:59], v180, v180 op_sel_hi:[0,0,0]
	v_mfma_scale_f32_16x16x128_f8f6f4 v[48:51], v[0:7], v[218:225], v[48:51], v180, v180 op_sel_hi:[0,0,0]
	v_mfma_scale_f32_16x16x128_f8f6f4 v[40:43], v[8:15], v[218:225], v[40:43], v180, v180 op_sel_hi:[0,0,0]
	s_setprio 0
	s_setprio 3
	v_mfma_scale_f32_16x16x128_f8f6f4 v[84:87], v[16:23], v[186:193], v[84:87], v180, v180 op_sel_hi:[0,0,0]
	v_mfma_scale_f32_16x16x128_f8f6f4 v[76:79], v[24:31], v[186:193], v[76:79], v180, v180 op_sel_hi:[0,0,0]
	v_mfma_scale_f32_16x16x128_f8f6f4 v[68:71], v[16:23], v[194:201], v[68:71], v180, v180 op_sel_hi:[0,0,0]
	v_mfma_scale_f32_16x16x128_f8f6f4 v[60:63], v[24:31], v[194:201], v[60:63], v180, v180 op_sel_hi:[0,0,0]
	v_mfma_scale_f32_16x16x128_f8f6f4 v[52:55], v[16:23], v[210:217], v[52:55], v180, v180 op_sel_hi:[0,0,0]
	v_mfma_scale_f32_16x16x128_f8f6f4 v[44:47], v[24:31], v[210:217], v[44:47], v180, v180 op_sel_hi:[0,0,0]
	v_mfma_scale_f32_16x16x128_f8f6f4 v[36:39], v[16:23], v[218:225], v[36:39], v180, v180 op_sel_hi:[0,0,0]
	v_mfma_scale_f32_16x16x128_f8f6f4 v[32:35], v[24:31], v[218:225], v[32:35], v180, v180 op_sel_hi:[0,0,0]
	s_barrier
	s_setprio 0
	s_cmpk_gt_u32 s35, 0x53
	s_mov_b32 s37, s6
	s_cbranch_scc1 .LBB0_1981
